# c25: c16 + register-bank experiment: in the four FFN-in K-loops the second MFMA input group is shifted by two registers (v[182:213]) so the two inputs start in different VGPR banks
# speedup vs baseline: 1.0118x; 1.0030x over previous
.LBB0_343:
	s_ashr_i32 s11, s10, 31
	s_lshl_b64 s[12:13], s[10:11], 20
	s_add_u32 s12, s26, s12
	s_addc_u32 s13, s27, s13
	s_and_b64 s[14:15], s[2:3], exec
	s_cselect_b32 s11, s13, s21
	s_cselect_b32 s75, s12, s20
	s_ashr_i32 s9, s8, 31
	s_lshl_b64 s[14:15], s[8:9], 20
	s_add_u32 s14, s28, s14
	s_addc_u32 s15, s29, s15
	s_and_b64 s[22:23], s[2:3], exec
	s_cselect_b32 s9, s15, s19
	s_cselect_b32 s76, s14, s18
	s_add_u32 s77, s18, 0x100
	s_addc_u32 s78, s19, 0
	s_add_u32 s18, s20, 0x80080
	s_addc_u32 s19, s21, 0
	s_add_u32 s79, s20, 0x100
	s_addc_u32 s80, s21, 0
	s_mov_b32 s81, -2
	v_mov_b32_e32 v252, v212
	v_mov_b32_e32 v253, v213
	ds_read_b128 v[148:151], v143
	ds_read_b128 v[152:155], v143 offset:1024
	ds_read_b128 v[156:159], v143 offset:2048
	ds_read_b128 v[160:163], v143 offset:3072
	ds_read_b128 v[164:167], v144
	ds_read_b128 v[168:171], v144 offset:1024
	ds_read_b128 v[172:175], v144 offset:2048
	ds_read_b128 v[176:179], v144 offset:3072
	s_cmp_eq_u32 s81, 28
	s_cselect_b32 s21, s9, s78
	s_cselect_b32 s20, s76, s77
	s_cselect_b32 s23, s11, s80
	s_cselect_b32 s22, s75, s79
	ds_read_b128 v[182:185], v145
	ds_read_b128 v[186:189], v145 offset:1024
	ds_read_b128 v[190:193], v145 offset:2048
	ds_read_b128 v[194:197], v145 offset:3072
	ds_read_b128 v[198:201], v145 offset:4096
	ds_read_b128 v[202:205], v145 offset:5120
	ds_read_b128 v[206:209], v145 offset:6144
	ds_read_b128 v[210:213], v145 offset:7168
	s_add_u32 s82, s18, 0xfff80000
	s_addc_u32 s83, s19, -1
	s_mov_b32 s86, m0
	s_mov_b32 m0, s64
	s_nop 0
	global_load_lds_dwordx4 v138, s[82:83]
	s_mov_b32 m0, s86
	s_nop 0
	s_mov_b32 s86, m0
	s_mov_b32 m0, s67
	s_nop 0
	global_load_lds_dwordx4 v140, s[82:83]
	s_mov_b32 m0, s86
	s_mov_b32 s82, m0
	s_mov_b32 m0, s65
	s_nop 0
	global_load_lds_dwordx4 v138, s[18:19]
	s_mov_b32 m0, s82
	s_nop 0
	s_mov_b32 s82, m0
	s_mov_b32 m0, s73
	s_nop 0
	global_load_lds_dwordx4 v140, s[18:19]
	s_mov_b32 m0, s82
	s_waitcnt vmcnt(8)
	s_waitcnt lgkmcnt(0)
	s_barrier
	s_setprio 1
	s_waitcnt lgkmcnt(7)
	v_mfma_f32_16x16x32_bf16 v[126:129], v[148:151], v[182:185], 0
	v_mfma_f32_16x16x32_bf16 v[126:129], v[152:155], v[186:189], v[126:129]
	s_waitcnt lgkmcnt(5)
	v_mfma_f32_16x16x32_bf16 v[122:125], v[156:159], v[182:185], 0
	v_mfma_f32_16x16x32_bf16 v[122:125], v[160:163], v[186:189], v[122:125]
	s_waitcnt lgkmcnt(3)
	v_mfma_f32_16x16x32_bf16 v[106:109], v[156:159], v[190:193], 0
	v_mfma_f32_16x16x32_bf16 v[106:109], v[160:163], v[194:197], v[106:109]
	s_waitcnt lgkmcnt(1)
	v_mfma_f32_16x16x32_bf16 v[110:113], v[148:151], v[190:193], 0
	v_mfma_f32_16x16x32_bf16 v[110:113], v[152:155], v[194:197], v[110:113]
	v_mfma_f32_16x16x32_bf16 v[94:97], v[148:151], v[198:201], 0
	v_mfma_f32_16x16x32_bf16 v[94:97], v[152:155], v[202:205], v[94:97]
	v_mfma_f32_16x16x32_bf16 v[90:93], v[156:159], v[198:201], 0
	v_mfma_f32_16x16x32_bf16 v[90:93], v[160:163], v[202:205], v[90:93]
	v_mfma_f32_16x16x32_bf16 v[74:77], v[156:159], v[206:209], 0
	v_mfma_f32_16x16x32_bf16 v[74:77], v[160:163], v[210:213], v[74:77]
	s_waitcnt lgkmcnt(0)
	v_mfma_f32_16x16x32_bf16 v[78:81], v[148:151], v[206:209], 0
	v_mfma_f32_16x16x32_bf16 v[78:81], v[152:155], v[210:213], v[78:81]
	s_setprio 0
	s_setprio 1
	v_mfma_f32_16x16x32_bf16 v[118:121], v[164:167], v[182:185], 0
	v_mfma_f32_16x16x32_bf16 v[118:121], v[168:171], v[186:189], v[118:121]
	v_mfma_f32_16x16x32_bf16 v[114:117], v[172:175], v[182:185], 0
	v_mfma_f32_16x16x32_bf16 v[114:117], v[176:179], v[186:189], v[114:117]
	v_mfma_f32_16x16x32_bf16 v[98:101], v[172:175], v[190:193], 0
	v_mfma_f32_16x16x32_bf16 v[98:101], v[176:179], v[194:197], v[98:101]
	v_mfma_f32_16x16x32_bf16 v[102:105], v[164:167], v[190:193], 0
	v_mfma_f32_16x16x32_bf16 v[102:105], v[168:171], v[194:197], v[102:105]
	v_mfma_f32_16x16x32_bf16 v[86:89], v[164:167], v[198:201], 0
	v_mfma_f32_16x16x32_bf16 v[86:89], v[168:171], v[202:205], v[86:89]
	v_mfma_f32_16x16x32_bf16 v[82:85], v[172:175], v[198:201], 0
	v_mfma_f32_16x16x32_bf16 v[82:85], v[176:179], v[202:205], v[82:85]
	v_mfma_f32_16x16x32_bf16 v[66:69], v[172:175], v[206:209], 0
	v_mfma_f32_16x16x32_bf16 v[66:69], v[176:179], v[210:213], v[66:69]
	s_setprio 2
	s_barrier
	v_mfma_f32_16x16x32_bf16 v[70:73], v[164:167], v[206:209], 0
	v_mfma_f32_16x16x32_bf16 v[70:73], v[168:171], v[210:213], v[70:73]
	s_setprio 0
	ds_read_b128 v[182:185], v145 offset:16384
	ds_read_b128 v[186:189], v145 offset:17408
	ds_read_b128 v[190:193], v145 offset:18432
	ds_read_b128 v[194:197], v145 offset:19456
	ds_read_b128 v[198:201], v145 offset:20480
	ds_read_b128 v[202:205], v145 offset:21504
	ds_read_b128 v[206:209], v145 offset:22528
	ds_read_b128 v[210:213], v145 offset:23552
	s_mov_b32 s82, m0
	s_mov_b32 m0, s35
	s_nop 0
	global_load_lds_dwordx4 v139, s[20:21]
	s_mov_b32 m0, s82
	s_nop 0
	s_mov_b32 s82, m0
	s_mov_b32 m0, s36
	s_nop 0
	global_load_lds_dwordx4 v141, s[20:21]
	s_mov_b32 m0, s82
	s_add_u32 s82, s20, 0x80000
	s_addc_u32 s83, s21, 0
	s_mov_b32 s86, m0
	s_mov_b32 m0, s37
	s_nop 0
	global_load_lds_dwordx4 v139, s[82:83]
	s_mov_b32 m0, s86
	s_nop 0
	s_mov_b32 s86, m0
	s_mov_b32 m0, s42
	s_nop 0
	global_load_lds_dwordx4 v141, s[82:83]
	s_mov_b32 m0, s86
	s_waitcnt vmcnt(4)
	s_waitcnt lgkmcnt(0)
	s_barrier
	s_setprio 1
	s_waitcnt lgkmcnt(7)
	v_mfma_f32_16x16x32_bf16 v[62:65], v[148:151], v[182:185], 0
	v_mfma_f32_16x16x32_bf16 v[62:65], v[152:155], v[186:189], v[62:65]
	s_waitcnt lgkmcnt(5)
	v_mfma_f32_16x16x32_bf16 v[58:61], v[156:159], v[182:185], 0
	v_mfma_f32_16x16x32_bf16 v[58:61], v[160:163], v[186:189], v[58:61]
	s_waitcnt lgkmcnt(3)
	v_mfma_f32_16x16x32_bf16 v[42:45], v[156:159], v[190:193], 0
	v_mfma_f32_16x16x32_bf16 v[42:45], v[160:163], v[194:197], v[42:45]
	s_waitcnt lgkmcnt(1)
	v_mfma_f32_16x16x32_bf16 v[46:49], v[148:151], v[190:193], 0
	v_mfma_f32_16x16x32_bf16 v[46:49], v[152:155], v[194:197], v[46:49]
	v_mfma_f32_16x16x32_bf16 v[30:33], v[148:151], v[198:201], 0
	v_mfma_f32_16x16x32_bf16 v[30:33], v[152:155], v[202:205], v[30:33]
	v_mfma_f32_16x16x32_bf16 v[26:29], v[156:159], v[198:201], 0
	v_mfma_f32_16x16x32_bf16 v[26:29], v[160:163], v[202:205], v[26:29]
	v_mfma_f32_16x16x32_bf16 v[10:13], v[156:159], v[206:209], 0
	v_mfma_f32_16x16x32_bf16 v[10:13], v[160:163], v[210:213], v[10:13]
	s_waitcnt lgkmcnt(0)
	v_mfma_f32_16x16x32_bf16 v[14:17], v[148:151], v[206:209], 0
	v_mfma_f32_16x16x32_bf16 v[14:17], v[152:155], v[210:213], v[14:17]
	s_setprio 0
	s_setprio 1
	v_mfma_f32_16x16x32_bf16 v[54:57], v[164:167], v[182:185], 0
	v_mfma_f32_16x16x32_bf16 v[54:57], v[168:171], v[186:189], v[54:57]
	v_mfma_f32_16x16x32_bf16 v[50:53], v[172:175], v[182:185], 0
	v_mfma_f32_16x16x32_bf16 v[50:53], v[176:179], v[186:189], v[50:53]
	v_mfma_f32_16x16x32_bf16 v[34:37], v[172:175], v[190:193], 0
	v_mfma_f32_16x16x32_bf16 v[34:37], v[176:179], v[194:197], v[34:37]
	v_mfma_f32_16x16x32_bf16 v[38:41], v[164:167], v[190:193], 0
	v_mfma_f32_16x16x32_bf16 v[38:41], v[168:171], v[194:197], v[38:41]
	v_mfma_f32_16x16x32_bf16 v[22:25], v[164:167], v[198:201], 0
	v_mfma_f32_16x16x32_bf16 v[22:25], v[168:171], v[202:205], v[22:25]
	v_mfma_f32_16x16x32_bf16 v[18:21], v[172:175], v[198:201], 0
	v_mfma_f32_16x16x32_bf16 v[18:21], v[176:179], v[202:205], v[18:21]
	v_mfma_f32_16x16x32_bf16 v[2:5], v[172:175], v[206:209], 0
	v_mfma_f32_16x16x32_bf16 v[2:5], v[176:179], v[210:213], v[2:5]
	s_setprio 2
	s_barrier
	v_mfma_f32_16x16x32_bf16 v[6:9], v[164:167], v[206:209], 0
	v_mfma_f32_16x16x32_bf16 v[6:9], v[168:171], v[210:213], v[6:9]
	s_setprio 0
	ds_read_b128 v[148:151], v146
	ds_read_b128 v[152:155], v146 offset:1024
	ds_read_b128 v[156:159], v146 offset:2048
	ds_read_b128 v[160:163], v146 offset:3072
	ds_read_b128 v[164:167], v147
	ds_read_b128 v[168:171], v147 offset:1024
	ds_read_b128 v[172:175], v147 offset:2048
	ds_read_b128 v[176:179], v147 offset:3072
	ds_read_b128 v[182:185], v145 offset:32768
	ds_read_b128 v[186:189], v145 offset:33792
	ds_read_b128 v[190:193], v145 offset:34816
	ds_read_b128 v[194:197], v145 offset:35840
	ds_read_b128 v[198:201], v145 offset:36864
	ds_read_b128 v[202:205], v145 offset:37888
	ds_read_b128 v[206:209], v145 offset:38912
	ds_read_b128 v[210:213], v145 offset:39936
	s_mov_b32 s82, m0
	s_mov_b32 m0, s31
	s_nop 0
	global_load_lds_dwordx4 v138, s[22:23]
	s_mov_b32 m0, s82
	s_nop 0
	s_mov_b32 s82, m0
	s_mov_b32 m0, s43
	s_nop 0
	global_load_lds_dwordx4 v140, s[22:23]
	s_mov_b32 m0, s82
	s_add_u32 s22, s22, 0x80000
	s_addc_u32 s23, s23, 0
	s_mov_b32 s82, m0
	s_mov_b32 m0, s46
	s_nop 0
	global_load_lds_dwordx4 v138, s[22:23]
	s_mov_b32 m0, s82
	s_nop 0
	s_mov_b32 s82, m0
	s_mov_b32 m0, s47
	s_nop 0
	global_load_lds_dwordx4 v140, s[22:23]
	s_mov_b32 m0, s82
	s_waitcnt vmcnt(8)
	s_waitcnt lgkmcnt(0)
	s_barrier
	s_setprio 1
	s_waitcnt lgkmcnt(7)
	v_mfma_f32_16x16x32_bf16 v[126:129], v[148:151], v[182:185], v[126:129]
	v_mfma_f32_16x16x32_bf16 v[126:129], v[152:155], v[186:189], v[126:129]
	s_waitcnt lgkmcnt(5)
	v_mfma_f32_16x16x32_bf16 v[122:125], v[156:159], v[182:185], v[122:125]
	v_mfma_f32_16x16x32_bf16 v[122:125], v[160:163], v[186:189], v[122:125]
	s_waitcnt lgkmcnt(3)
	v_mfma_f32_16x16x32_bf16 v[106:109], v[156:159], v[190:193], v[106:109]
	v_mfma_f32_16x16x32_bf16 v[106:109], v[160:163], v[194:197], v[106:109]
	s_waitcnt lgkmcnt(1)
	v_mfma_f32_16x16x32_bf16 v[110:113], v[148:151], v[190:193], v[110:113]
	v_mfma_f32_16x16x32_bf16 v[110:113], v[152:155], v[194:197], v[110:113]
	v_mfma_f32_16x16x32_bf16 v[94:97], v[148:151], v[198:201], v[94:97]
	v_mfma_f32_16x16x32_bf16 v[94:97], v[152:155], v[202:205], v[94:97]
	v_mfma_f32_16x16x32_bf16 v[90:93], v[156:159], v[198:201], v[90:93]
	v_mfma_f32_16x16x32_bf16 v[90:93], v[160:163], v[202:205], v[90:93]
	v_mfma_f32_16x16x32_bf16 v[74:77], v[156:159], v[206:209], v[74:77]
	v_mfma_f32_16x16x32_bf16 v[74:77], v[160:163], v[210:213], v[74:77]
	s_waitcnt lgkmcnt(0)
	v_mfma_f32_16x16x32_bf16 v[78:81], v[148:151], v[206:209], v[78:81]
	v_mfma_f32_16x16x32_bf16 v[78:81], v[152:155], v[210:213], v[78:81]
	s_setprio 0
	s_setprio 1
	v_mfma_f32_16x16x32_bf16 v[118:121], v[164:167], v[182:185], v[118:121]
	v_mfma_f32_16x16x32_bf16 v[118:121], v[168:171], v[186:189], v[118:121]
	v_mfma_f32_16x16x32_bf16 v[114:117], v[172:175], v[182:185], v[114:117]
	v_mfma_f32_16x16x32_bf16 v[114:117], v[176:179], v[186:189], v[114:117]
	v_mfma_f32_16x16x32_bf16 v[98:101], v[172:175], v[190:193], v[98:101]
	v_mfma_f32_16x16x32_bf16 v[98:101], v[176:179], v[194:197], v[98:101]
	v_mfma_f32_16x16x32_bf16 v[102:105], v[164:167], v[190:193], v[102:105]
	v_mfma_f32_16x16x32_bf16 v[102:105], v[168:171], v[194:197], v[102:105]
	v_mfma_f32_16x16x32_bf16 v[86:89], v[164:167], v[198:201], v[86:89]
	v_mfma_f32_16x16x32_bf16 v[86:89], v[168:171], v[202:205], v[86:89]
	v_mfma_f32_16x16x32_bf16 v[82:85], v[172:175], v[198:201], v[82:85]
	v_mfma_f32_16x16x32_bf16 v[82:85], v[176:179], v[202:205], v[82:85]
	v_mfma_f32_16x16x32_bf16 v[66:69], v[172:175], v[206:209], v[66:69]
	v_mfma_f32_16x16x32_bf16 v[66:69], v[176:179], v[210:213], v[66:69]
	s_setprio 2
	s_barrier
	v_mfma_f32_16x16x32_bf16 v[70:73], v[164:167], v[206:209], v[70:73]
	v_mfma_f32_16x16x32_bf16 v[70:73], v[168:171], v[210:213], v[70:73]
	s_setprio 0
	ds_read_b128 v[182:185], v145 offset:49152
	ds_read_b128 v[186:189], v145 offset:50176
	ds_read_b128 v[190:193], v145 offset:51200
	ds_read_b128 v[194:197], v145 offset:52224
	ds_read_b128 v[198:201], v145 offset:53248
	ds_read_b128 v[202:205], v145 offset:54272
	ds_read_b128 v[206:209], v145 offset:55296
	ds_read_b128 v[210:213], v145 offset:56320
	s_add_u32 s22, s20, 0x80
	s_addc_u32 s23, s21, 0
	s_mov_b32 s82, m0
	s_mov_b32 m0, s48
	s_nop 0
	global_load_lds_dwordx4 v139, s[22:23]
	s_mov_b32 m0, s82
	s_add_u32 s20, s20, 0x80080
	s_mov_b32 s82, m0
	s_mov_b32 m0, s49
	s_nop 0
	global_load_lds_dwordx4 v141, s[22:23]
	s_mov_b32 m0, s82
	s_addc_u32 s21, s21, 0
	s_mov_b32 s22, m0
	s_mov_b32 m0, s56
	s_nop 0
	global_load_lds_dwordx4 v139, s[20:21]
	s_mov_b32 m0, s22
	s_nop 0
	s_mov_b32 s22, m0
	s_mov_b32 m0, s57
	s_nop 0
	global_load_lds_dwordx4 v141, s[20:21]
	s_mov_b32 m0, s22
	s_waitcnt vmcnt(4)
	s_waitcnt lgkmcnt(0)
	s_barrier
	s_setprio 1
	s_waitcnt lgkmcnt(7)
	v_mfma_f32_16x16x32_bf16 v[62:65], v[148:151], v[182:185], v[62:65]
	v_mfma_f32_16x16x32_bf16 v[62:65], v[152:155], v[186:189], v[62:65]
	s_waitcnt lgkmcnt(5)
	v_mfma_f32_16x16x32_bf16 v[58:61], v[156:159], v[182:185], v[58:61]
	v_mfma_f32_16x16x32_bf16 v[58:61], v[160:163], v[186:189], v[58:61]
	s_waitcnt lgkmcnt(3)
	v_mfma_f32_16x16x32_bf16 v[42:45], v[156:159], v[190:193], v[42:45]
	v_mfma_f32_16x16x32_bf16 v[42:45], v[160:163], v[194:197], v[42:45]
	s_waitcnt lgkmcnt(1)
	v_mfma_f32_16x16x32_bf16 v[46:49], v[148:151], v[190:193], v[46:49]
	v_mfma_f32_16x16x32_bf16 v[46:49], v[152:155], v[194:197], v[46:49]
	v_mfma_f32_16x16x32_bf16 v[30:33], v[148:151], v[198:201], v[30:33]
	v_mfma_f32_16x16x32_bf16 v[30:33], v[152:155], v[202:205], v[30:33]
	v_mfma_f32_16x16x32_bf16 v[26:29], v[156:159], v[198:201], v[26:29]
	v_mfma_f32_16x16x32_bf16 v[26:29], v[160:163], v[202:205], v[26:29]
	v_mfma_f32_16x16x32_bf16 v[10:13], v[156:159], v[206:209], v[10:13]
	v_mfma_f32_16x16x32_bf16 v[10:13], v[160:163], v[210:213], v[10:13]
	s_waitcnt lgkmcnt(0)
	v_mfma_f32_16x16x32_bf16 v[14:17], v[148:151], v[206:209], v[14:17]
	v_mfma_f32_16x16x32_bf16 v[14:17], v[152:155], v[210:213], v[14:17]
	s_setprio 0
	s_setprio 1
	v_mfma_f32_16x16x32_bf16 v[54:57], v[164:167], v[182:185], v[54:57]
	v_mfma_f32_16x16x32_bf16 v[54:57], v[168:171], v[186:189], v[54:57]
	v_mfma_f32_16x16x32_bf16 v[50:53], v[172:175], v[182:185], v[50:53]
	v_mfma_f32_16x16x32_bf16 v[50:53], v[176:179], v[186:189], v[50:53]
	v_mfma_f32_16x16x32_bf16 v[34:37], v[172:175], v[190:193], v[34:37]
	v_mfma_f32_16x16x32_bf16 v[34:37], v[176:179], v[194:197], v[34:37]
	v_mfma_f32_16x16x32_bf16 v[38:41], v[164:167], v[190:193], v[38:41]
	v_mfma_f32_16x16x32_bf16 v[38:41], v[168:171], v[194:197], v[38:41]
	v_mfma_f32_16x16x32_bf16 v[22:25], v[164:167], v[198:201], v[22:25]
	v_mfma_f32_16x16x32_bf16 v[22:25], v[168:171], v[202:205], v[22:25]
	v_mfma_f32_16x16x32_bf16 v[18:21], v[172:175], v[198:201], v[18:21]
	v_mfma_f32_16x16x32_bf16 v[18:21], v[176:179], v[202:205], v[18:21]
	v_mfma_f32_16x16x32_bf16 v[2:5], v[172:175], v[206:209], v[2:5]
	v_mfma_f32_16x16x32_bf16 v[2:5], v[176:179], v[210:213], v[2:5]
	s_setprio 2
	s_barrier
	v_mfma_f32_16x16x32_bf16 v[6:9], v[164:167], v[206:209], v[6:9]
	v_mfma_f32_16x16x32_bf16 v[6:9], v[168:171], v[210:213], v[6:9]
	s_setprio 0
	s_add_i32 s81, s81, 2
	s_add_u32 s77, s77, 0x100
	s_addc_u32 s78, s78, 0
	s_add_u32 s18, s18, 0x100
	s_addc_u32 s19, s19, 0
	s_add_u32 s79, s79, 0x100
	s_addc_u32 s80, s80, 0
	s_cmp_gt_u32 s81, 29
	.p2align 6
.LBB0_344:
	ds_read_b128 v[148:151], v143
	ds_read_b128 v[152:155], v143 offset:1024
	ds_read_b128 v[156:159], v143 offset:2048
	ds_read_b128 v[160:163], v143 offset:3072
	ds_read_b128 v[164:167], v144
	ds_read_b128 v[168:171], v144 offset:1024
	ds_read_b128 v[172:175], v144 offset:2048
	ds_read_b128 v[176:179], v144 offset:3072
	s_cmp_eq_u32 s81, 28
	s_cselect_b32 s21, s9, s78
	s_cselect_b32 s20, s76, s77
	s_cselect_b32 s23, s11, s80
	s_cselect_b32 s22, s75, s79
	ds_read_b128 v[182:185], v145
	ds_read_b128 v[186:189], v145 offset:1024
	ds_read_b128 v[190:193], v145 offset:2048
	ds_read_b128 v[194:197], v145 offset:3072
	ds_read_b128 v[198:201], v145 offset:4096
	ds_read_b128 v[202:205], v145 offset:5120
	ds_read_b128 v[206:209], v145 offset:6144
	ds_read_b128 v[210:213], v145 offset:7168
	s_add_u32 s82, s18, 0xfff80000
	s_addc_u32 s83, s19, -1
	s_mov_b32 s86, m0
	s_mov_b32 m0, s64
	s_nop 0
	global_load_lds_dwordx4 v138, s[82:83]
	s_mov_b32 m0, s86
	s_nop 0
	s_mov_b32 s86, m0
	s_mov_b32 m0, s67
	s_nop 0
	global_load_lds_dwordx4 v140, s[82:83]
	s_mov_b32 m0, s86
	s_mov_b32 s82, m0
	s_mov_b32 m0, s65
	s_nop 0
	global_load_lds_dwordx4 v138, s[18:19]
	s_mov_b32 m0, s82
	s_nop 0
	s_mov_b32 s82, m0
	s_mov_b32 m0, s73
	s_nop 0
	global_load_lds_dwordx4 v140, s[18:19]
	s_mov_b32 m0, s82
	s_waitcnt vmcnt(8)
	s_waitcnt lgkmcnt(0)
	s_barrier
	s_setprio 1
	s_waitcnt lgkmcnt(7)
	v_mfma_f32_16x16x32_bf16 v[126:129], v[148:151], v[182:185], v[126:129]
	v_mfma_f32_16x16x32_bf16 v[126:129], v[152:155], v[186:189], v[126:129]
	s_waitcnt lgkmcnt(5)
	v_mfma_f32_16x16x32_bf16 v[122:125], v[156:159], v[182:185], v[122:125]
	v_mfma_f32_16x16x32_bf16 v[122:125], v[160:163], v[186:189], v[122:125]
	s_waitcnt lgkmcnt(3)
	v_mfma_f32_16x16x32_bf16 v[106:109], v[156:159], v[190:193], v[106:109]
	v_mfma_f32_16x16x32_bf16 v[106:109], v[160:163], v[194:197], v[106:109]
	s_waitcnt lgkmcnt(1)
	v_mfma_f32_16x16x32_bf16 v[110:113], v[148:151], v[190:193], v[110:113]
	v_mfma_f32_16x16x32_bf16 v[110:113], v[152:155], v[194:197], v[110:113]
	v_mfma_f32_16x16x32_bf16 v[94:97], v[148:151], v[198:201], v[94:97]
	v_mfma_f32_16x16x32_bf16 v[94:97], v[152:155], v[202:205], v[94:97]
	v_mfma_f32_16x16x32_bf16 v[90:93], v[156:159], v[198:201], v[90:93]
	v_mfma_f32_16x16x32_bf16 v[90:93], v[160:163], v[202:205], v[90:93]
	v_mfma_f32_16x16x32_bf16 v[74:77], v[156:159], v[206:209], v[74:77]
	v_mfma_f32_16x16x32_bf16 v[74:77], v[160:163], v[210:213], v[74:77]
	s_waitcnt lgkmcnt(0)
	v_mfma_f32_16x16x32_bf16 v[78:81], v[148:151], v[206:209], v[78:81]
	v_mfma_f32_16x16x32_bf16 v[78:81], v[152:155], v[210:213], v[78:81]
	s_setprio 0
	s_setprio 1
	v_mfma_f32_16x16x32_bf16 v[118:121], v[164:167], v[182:185], v[118:121]
	v_mfma_f32_16x16x32_bf16 v[118:121], v[168:171], v[186:189], v[118:121]
	v_mfma_f32_16x16x32_bf16 v[114:117], v[172:175], v[182:185], v[114:117]
	v_mfma_f32_16x16x32_bf16 v[114:117], v[176:179], v[186:189], v[114:117]
	v_mfma_f32_16x16x32_bf16 v[98:101], v[172:175], v[190:193], v[98:101]
	v_mfma_f32_16x16x32_bf16 v[98:101], v[176:179], v[194:197], v[98:101]
	v_mfma_f32_16x16x32_bf16 v[102:105], v[164:167], v[190:193], v[102:105]
	v_mfma_f32_16x16x32_bf16 v[102:105], v[168:171], v[194:197], v[102:105]
	v_mfma_f32_16x16x32_bf16 v[86:89], v[164:167], v[198:201], v[86:89]
	v_mfma_f32_16x16x32_bf16 v[86:89], v[168:171], v[202:205], v[86:89]
	v_mfma_f32_16x16x32_bf16 v[82:85], v[172:175], v[198:201], v[82:85]
	v_mfma_f32_16x16x32_bf16 v[82:85], v[176:179], v[202:205], v[82:85]
	v_mfma_f32_16x16x32_bf16 v[66:69], v[172:175], v[206:209], v[66:69]
	v_mfma_f32_16x16x32_bf16 v[66:69], v[176:179], v[210:213], v[66:69]
	s_setprio 2
	s_barrier
	v_mfma_f32_16x16x32_bf16 v[70:73], v[164:167], v[206:209], v[70:73]
	v_mfma_f32_16x16x32_bf16 v[70:73], v[168:171], v[210:213], v[70:73]
	s_setprio 0
	ds_read_b128 v[182:185], v145 offset:16384
	ds_read_b128 v[186:189], v145 offset:17408
	ds_read_b128 v[190:193], v145 offset:18432
	ds_read_b128 v[194:197], v145 offset:19456
	ds_read_b128 v[198:201], v145 offset:20480
	ds_read_b128 v[202:205], v145 offset:21504
	ds_read_b128 v[206:209], v145 offset:22528
	ds_read_b128 v[210:213], v145 offset:23552
	s_mov_b32 s82, m0
	s_mov_b32 m0, s35
	s_nop 0
	global_load_lds_dwordx4 v139, s[20:21]
	s_mov_b32 m0, s82
	s_nop 0
	s_mov_b32 s82, m0
	s_mov_b32 m0, s36
	s_nop 0
	global_load_lds_dwordx4 v141, s[20:21]
	s_mov_b32 m0, s82
	s_add_u32 s82, s20, 0x80000
	s_addc_u32 s83, s21, 0
	s_mov_b32 s86, m0
	s_mov_b32 m0, s37
	s_nop 0
	global_load_lds_dwordx4 v139, s[82:83]
	s_mov_b32 m0, s86
	s_nop 0
	s_mov_b32 s86, m0
	s_mov_b32 m0, s42
	s_nop 0
	global_load_lds_dwordx4 v141, s[82:83]
	s_mov_b32 m0, s86
	s_waitcnt vmcnt(4)
	s_waitcnt lgkmcnt(0)
	s_barrier
	s_setprio 1
	s_waitcnt lgkmcnt(7)
	v_mfma_f32_16x16x32_bf16 v[62:65], v[148:151], v[182:185], v[62:65]
	v_mfma_f32_16x16x32_bf16 v[62:65], v[152:155], v[186:189], v[62:65]
	s_waitcnt lgkmcnt(5)
	v_mfma_f32_16x16x32_bf16 v[58:61], v[156:159], v[182:185], v[58:61]
	v_mfma_f32_16x16x32_bf16 v[58:61], v[160:163], v[186:189], v[58:61]
	s_waitcnt lgkmcnt(3)
	v_mfma_f32_16x16x32_bf16 v[42:45], v[156:159], v[190:193], v[42:45]
	v_mfma_f32_16x16x32_bf16 v[42:45], v[160:163], v[194:197], v[42:45]
	s_waitcnt lgkmcnt(1)
	v_mfma_f32_16x16x32_bf16 v[46:49], v[148:151], v[190:193], v[46:49]
	v_mfma_f32_16x16x32_bf16 v[46:49], v[152:155], v[194:197], v[46:49]
	v_mfma_f32_16x16x32_bf16 v[30:33], v[148:151], v[198:201], v[30:33]
	v_mfma_f32_16x16x32_bf16 v[30:33], v[152:155], v[202:205], v[30:33]
	v_mfma_f32_16x16x32_bf16 v[26:29], v[156:159], v[198:201], v[26:29]
	v_mfma_f32_16x16x32_bf16 v[26:29], v[160:163], v[202:205], v[26:29]
	v_mfma_f32_16x16x32_bf16 v[10:13], v[156:159], v[206:209], v[10:13]
	v_mfma_f32_16x16x32_bf16 v[10:13], v[160:163], v[210:213], v[10:13]
	s_waitcnt lgkmcnt(0)
	v_mfma_f32_16x16x32_bf16 v[14:17], v[148:151], v[206:209], v[14:17]
	v_mfma_f32_16x16x32_bf16 v[14:17], v[152:155], v[210:213], v[14:17]
	s_setprio 0
	s_setprio 1
	v_mfma_f32_16x16x32_bf16 v[54:57], v[164:167], v[182:185], v[54:57]
	v_mfma_f32_16x16x32_bf16 v[54:57], v[168:171], v[186:189], v[54:57]
	v_mfma_f32_16x16x32_bf16 v[50:53], v[172:175], v[182:185], v[50:53]
	v_mfma_f32_16x16x32_bf16 v[50:53], v[176:179], v[186:189], v[50:53]
	v_mfma_f32_16x16x32_bf16 v[34:37], v[172:175], v[190:193], v[34:37]
	v_mfma_f32_16x16x32_bf16 v[34:37], v[176:179], v[194:197], v[34:37]
	v_mfma_f32_16x16x32_bf16 v[38:41], v[164:167], v[190:193], v[38:41]
	v_mfma_f32_16x16x32_bf16 v[38:41], v[168:171], v[194:197], v[38:41]
	v_mfma_f32_16x16x32_bf16 v[22:25], v[164:167], v[198:201], v[22:25]
	v_mfma_f32_16x16x32_bf16 v[22:25], v[168:171], v[202:205], v[22:25]
	v_mfma_f32_16x16x32_bf16 v[18:21], v[172:175], v[198:201], v[18:21]
	v_mfma_f32_16x16x32_bf16 v[18:21], v[176:179], v[202:205], v[18:21]
	v_mfma_f32_16x16x32_bf16 v[2:5], v[172:175], v[206:209], v[2:5]
	v_mfma_f32_16x16x32_bf16 v[2:5], v[176:179], v[210:213], v[2:5]
	s_setprio 2
	s_barrier
	v_mfma_f32_16x16x32_bf16 v[6:9], v[164:167], v[206:209], v[6:9]
	v_mfma_f32_16x16x32_bf16 v[6:9], v[168:171], v[210:213], v[6:9]
	s_setprio 0
	ds_read_b128 v[148:151], v146
	ds_read_b128 v[152:155], v146 offset:1024
	ds_read_b128 v[156:159], v146 offset:2048
	ds_read_b128 v[160:163], v146 offset:3072
	ds_read_b128 v[164:167], v147
	ds_read_b128 v[168:171], v147 offset:1024
	ds_read_b128 v[172:175], v147 offset:2048
	ds_read_b128 v[176:179], v147 offset:3072
	ds_read_b128 v[182:185], v145 offset:32768
	ds_read_b128 v[186:189], v145 offset:33792
	ds_read_b128 v[190:193], v145 offset:34816
	ds_read_b128 v[194:197], v145 offset:35840
	ds_read_b128 v[198:201], v145 offset:36864
	ds_read_b128 v[202:205], v145 offset:37888
	ds_read_b128 v[206:209], v145 offset:38912
	ds_read_b128 v[210:213], v145 offset:39936
	s_mov_b32 s82, m0
	s_mov_b32 m0, s31
	s_nop 0
	global_load_lds_dwordx4 v138, s[22:23]
	s_mov_b32 m0, s82
	s_nop 0
	s_mov_b32 s82, m0
	s_mov_b32 m0, s43
	s_nop 0
	global_load_lds_dwordx4 v140, s[22:23]
	s_mov_b32 m0, s82
	s_add_u32 s22, s22, 0x80000
	s_addc_u32 s23, s23, 0
	s_mov_b32 s82, m0
	s_mov_b32 m0, s46
	s_nop 0
	global_load_lds_dwordx4 v138, s[22:23]
	s_mov_b32 m0, s82
	s_nop 0
	s_mov_b32 s82, m0
	s_mov_b32 m0, s47
	s_nop 0
	global_load_lds_dwordx4 v140, s[22:23]
	s_mov_b32 m0, s82
	s_waitcnt vmcnt(8)
	s_waitcnt lgkmcnt(0)
	s_barrier
	s_setprio 1
	s_waitcnt lgkmcnt(7)
	v_mfma_f32_16x16x32_bf16 v[126:129], v[148:151], v[182:185], v[126:129]
	v_mfma_f32_16x16x32_bf16 v[126:129], v[152:155], v[186:189], v[126:129]
	s_waitcnt lgkmcnt(5)
	v_mfma_f32_16x16x32_bf16 v[122:125], v[156:159], v[182:185], v[122:125]
	v_mfma_f32_16x16x32_bf16 v[122:125], v[160:163], v[186:189], v[122:125]
	s_waitcnt lgkmcnt(3)
	v_mfma_f32_16x16x32_bf16 v[106:109], v[156:159], v[190:193], v[106:109]
	v_mfma_f32_16x16x32_bf16 v[106:109], v[160:163], v[194:197], v[106:109]
	s_waitcnt lgkmcnt(1)
	v_mfma_f32_16x16x32_bf16 v[110:113], v[148:151], v[190:193], v[110:113]
	v_mfma_f32_16x16x32_bf16 v[110:113], v[152:155], v[194:197], v[110:113]
	v_mfma_f32_16x16x32_bf16 v[94:97], v[148:151], v[198:201], v[94:97]
	v_mfma_f32_16x16x32_bf16 v[94:97], v[152:155], v[202:205], v[94:97]
	v_mfma_f32_16x16x32_bf16 v[90:93], v[156:159], v[198:201], v[90:93]
	v_mfma_f32_16x16x32_bf16 v[90:93], v[160:163], v[202:205], v[90:93]
	v_mfma_f32_16x16x32_bf16 v[74:77], v[156:159], v[206:209], v[74:77]
	v_mfma_f32_16x16x32_bf16 v[74:77], v[160:163], v[210:213], v[74:77]
	s_waitcnt lgkmcnt(0)
	v_mfma_f32_16x16x32_bf16 v[78:81], v[148:151], v[206:209], v[78:81]
	v_mfma_f32_16x16x32_bf16 v[78:81], v[152:155], v[210:213], v[78:81]
	s_setprio 0
	s_setprio 1
	v_mfma_f32_16x16x32_bf16 v[118:121], v[164:167], v[182:185], v[118:121]
	v_mfma_f32_16x16x32_bf16 v[118:121], v[168:171], v[186:189], v[118:121]
	v_mfma_f32_16x16x32_bf16 v[114:117], v[172:175], v[182:185], v[114:117]
	v_mfma_f32_16x16x32_bf16 v[114:117], v[176:179], v[186:189], v[114:117]
	v_mfma_f32_16x16x32_bf16 v[98:101], v[172:175], v[190:193], v[98:101]
	v_mfma_f32_16x16x32_bf16 v[98:101], v[176:179], v[194:197], v[98:101]
	v_mfma_f32_16x16x32_bf16 v[102:105], v[164:167], v[190:193], v[102:105]
	v_mfma_f32_16x16x32_bf16 v[102:105], v[168:171], v[194:197], v[102:105]
	v_mfma_f32_16x16x32_bf16 v[86:89], v[164:167], v[198:201], v[86:89]
	v_mfma_f32_16x16x32_bf16 v[86:89], v[168:171], v[202:205], v[86:89]
	v_mfma_f32_16x16x32_bf16 v[82:85], v[172:175], v[198:201], v[82:85]
	v_mfma_f32_16x16x32_bf16 v[82:85], v[176:179], v[202:205], v[82:85]
	v_mfma_f32_16x16x32_bf16 v[66:69], v[172:175], v[206:209], v[66:69]
	v_mfma_f32_16x16x32_bf16 v[66:69], v[176:179], v[210:213], v[66:69]
	s_setprio 2
	s_barrier
	v_mfma_f32_16x16x32_bf16 v[70:73], v[164:167], v[206:209], v[70:73]
	v_mfma_f32_16x16x32_bf16 v[70:73], v[168:171], v[210:213], v[70:73]
	s_setprio 0
	ds_read_b128 v[182:185], v145 offset:49152
	ds_read_b128 v[186:189], v145 offset:50176
	ds_read_b128 v[190:193], v145 offset:51200
	ds_read_b128 v[194:197], v145 offset:52224
	ds_read_b128 v[198:201], v145 offset:53248
	ds_read_b128 v[202:205], v145 offset:54272
	ds_read_b128 v[206:209], v145 offset:55296
	ds_read_b128 v[210:213], v145 offset:56320
	s_add_u32 s22, s20, 0x80
	s_addc_u32 s23, s21, 0
	s_mov_b32 s82, m0
	s_mov_b32 m0, s48
	s_nop 0
	global_load_lds_dwordx4 v139, s[22:23]
	s_mov_b32 m0, s82
	s_add_u32 s20, s20, 0x80080
	s_mov_b32 s82, m0
	s_mov_b32 m0, s49
	s_nop 0
	global_load_lds_dwordx4 v141, s[22:23]
	s_mov_b32 m0, s82
	s_addc_u32 s21, s21, 0
	s_mov_b32 s22, m0
	s_mov_b32 m0, s56
	s_nop 0
	global_load_lds_dwordx4 v139, s[20:21]
	s_mov_b32 m0, s22
	s_nop 0
	s_mov_b32 s22, m0
	s_mov_b32 m0, s57
	s_nop 0
	global_load_lds_dwordx4 v141, s[20:21]
	s_mov_b32 m0, s22
	s_waitcnt vmcnt(4)
	s_waitcnt lgkmcnt(0)
	s_barrier
	s_setprio 1
	s_waitcnt lgkmcnt(7)
	v_mfma_f32_16x16x32_bf16 v[62:65], v[148:151], v[182:185], v[62:65]
	v_mfma_f32_16x16x32_bf16 v[62:65], v[152:155], v[186:189], v[62:65]
	s_waitcnt lgkmcnt(5)
	v_mfma_f32_16x16x32_bf16 v[58:61], v[156:159], v[182:185], v[58:61]
	v_mfma_f32_16x16x32_bf16 v[58:61], v[160:163], v[186:189], v[58:61]
	s_waitcnt lgkmcnt(3)
	v_mfma_f32_16x16x32_bf16 v[42:45], v[156:159], v[190:193], v[42:45]
	v_mfma_f32_16x16x32_bf16 v[42:45], v[160:163], v[194:197], v[42:45]
	s_waitcnt lgkmcnt(1)
	v_mfma_f32_16x16x32_bf16 v[46:49], v[148:151], v[190:193], v[46:49]
	v_mfma_f32_16x16x32_bf16 v[46:49], v[152:155], v[194:197], v[46:49]
	v_mfma_f32_16x16x32_bf16 v[30:33], v[148:151], v[198:201], v[30:33]
	v_mfma_f32_16x16x32_bf16 v[30:33], v[152:155], v[202:205], v[30:33]
	v_mfma_f32_16x16x32_bf16 v[26:29], v[156:159], v[198:201], v[26:29]
	v_mfma_f32_16x16x32_bf16 v[26:29], v[160:163], v[202:205], v[26:29]
	v_mfma_f32_16x16x32_bf16 v[10:13], v[156:159], v[206:209], v[10:13]
	v_mfma_f32_16x16x32_bf16 v[10:13], v[160:163], v[210:213], v[10:13]
	s_waitcnt lgkmcnt(0)
	v_mfma_f32_16x16x32_bf16 v[14:17], v[148:151], v[206:209], v[14:17]
	v_mfma_f32_16x16x32_bf16 v[14:17], v[152:155], v[210:213], v[14:17]
	s_setprio 0
	s_setprio 1
	v_mfma_f32_16x16x32_bf16 v[54:57], v[164:167], v[182:185], v[54:57]
	v_mfma_f32_16x16x32_bf16 v[54:57], v[168:171], v[186:189], v[54:57]
	v_mfma_f32_16x16x32_bf16 v[50:53], v[172:175], v[182:185], v[50:53]
	v_mfma_f32_16x16x32_bf16 v[50:53], v[176:179], v[186:189], v[50:53]
	v_mfma_f32_16x16x32_bf16 v[34:37], v[172:175], v[190:193], v[34:37]
	v_mfma_f32_16x16x32_bf16 v[34:37], v[176:179], v[194:197], v[34:37]
	v_mfma_f32_16x16x32_bf16 v[38:41], v[164:167], v[190:193], v[38:41]
	v_mfma_f32_16x16x32_bf16 v[38:41], v[168:171], v[194:197], v[38:41]
	v_mfma_f32_16x16x32_bf16 v[22:25], v[164:167], v[198:201], v[22:25]
	v_mfma_f32_16x16x32_bf16 v[22:25], v[168:171], v[202:205], v[22:25]
	v_mfma_f32_16x16x32_bf16 v[18:21], v[172:175], v[198:201], v[18:21]
	v_mfma_f32_16x16x32_bf16 v[18:21], v[176:179], v[202:205], v[18:21]
	v_mfma_f32_16x16x32_bf16 v[2:5], v[172:175], v[206:209], v[2:5]
	v_mfma_f32_16x16x32_bf16 v[2:5], v[176:179], v[210:213], v[2:5]
	s_setprio 2
	s_barrier
	v_mfma_f32_16x16x32_bf16 v[6:9], v[164:167], v[206:209], v[6:9]
	v_mfma_f32_16x16x32_bf16 v[6:9], v[168:171], v[210:213], v[6:9]
	s_setprio 0
	s_add_i32 s81, s81, 2
	s_add_u32 s77, s77, 0x100
	s_addc_u32 s78, s78, 0
	s_add_u32 s18, s18, 0x100
	s_addc_u32 s19, s19, 0
	s_add_u32 s79, s79, 0x100
	s_addc_u32 s80, s80, 0
	s_cmp_gt_u32 s81, 29
	s_cbranch_scc0 .LBB0_344
	v_mov_b32_e32 v212, v252
	v_mov_b32_e32 v213, v253
	s_and_b64 vcc, exec, s[6:7]
	s_cbranch_vccz .LBB0_347
	s_barrier

.LBB0_1223:
	s_ashr_i32 s11, s10, 31
	s_lshl_b64 s[12:13], s[10:11], 20
	s_add_u32 s12, s26, s12
	s_addc_u32 s13, s27, s13
	s_and_b64 s[14:15], s[2:3], exec
	s_cselect_b32 s11, s13, s21
	s_cselect_b32 s66, s12, s20
	s_ashr_i32 s9, s8, 31
	s_lshl_b64 s[14:15], s[8:9], 20
	s_add_u32 s14, s28, s14
	s_addc_u32 s15, s29, s15
	s_and_b64 s[22:23], s[2:3], exec
	s_cselect_b32 s9, s15, s19
	s_cselect_b32 s67, s14, s18
	s_add_u32 s73, s18, 0x100
	s_addc_u32 s74, s19, 0
	s_add_u32 s18, s20, 0x80080
	s_addc_u32 s19, s21, 0
	s_add_u32 s75, s20, 0x100
	s_addc_u32 s76, s21, 0
	s_mov_b32 s77, -2
	v_mov_b32_e32 v252, v212
	v_mov_b32_e32 v253, v213
	ds_read_b128 v[148:151], v143
	ds_read_b128 v[152:155], v143 offset:1024
	ds_read_b128 v[156:159], v143 offset:2048
	ds_read_b128 v[160:163], v143 offset:3072
	ds_read_b128 v[164:167], v144
	ds_read_b128 v[168:171], v144 offset:1024
	ds_read_b128 v[172:175], v144 offset:2048
	ds_read_b128 v[176:179], v144 offset:3072
	s_cmp_eq_u32 s77, 28
	s_cselect_b32 s21, s9, s74
	s_cselect_b32 s20, s67, s73
	s_cselect_b32 s23, s11, s76
	s_cselect_b32 s22, s66, s75
	ds_read_b128 v[182:185], v145
	ds_read_b128 v[186:189], v145 offset:1024
	ds_read_b128 v[190:193], v145 offset:2048
	ds_read_b128 v[194:197], v145 offset:3072
	ds_read_b128 v[198:201], v145 offset:4096
	ds_read_b128 v[202:205], v145 offset:5120
	ds_read_b128 v[206:209], v145 offset:6144
	ds_read_b128 v[210:213], v145 offset:7168
	s_add_u32 s78, s18, 0xfff80000
	s_addc_u32 s79, s19, -1
	s_mov_b32 s80, m0
	s_mov_b32 m0, s56
	s_nop 0
	global_load_lds_dwordx4 v138, s[78:79]
	s_mov_b32 m0, s80
	s_nop 0
	s_mov_b32 s80, m0
	s_mov_b32 m0, s59
	s_nop 0
	global_load_lds_dwordx4 v140, s[78:79]
	s_mov_b32 m0, s80
	s_mov_b32 s78, m0
	s_mov_b32 m0, s57
	s_nop 0
	global_load_lds_dwordx4 v138, s[18:19]
	s_mov_b32 m0, s78
	s_nop 0
	s_mov_b32 s78, m0
	s_mov_b32 m0, s64
	s_nop 0
	global_load_lds_dwordx4 v140, s[18:19]
	s_mov_b32 m0, s78
	s_waitcnt vmcnt(8)
	s_waitcnt lgkmcnt(0)
	s_barrier
	s_setprio 1
	s_waitcnt lgkmcnt(7)
	v_mfma_f32_16x16x32_bf16 v[126:129], v[148:151], v[182:185], 0
	v_mfma_f32_16x16x32_bf16 v[126:129], v[152:155], v[186:189], v[126:129]
	s_waitcnt lgkmcnt(5)
	v_mfma_f32_16x16x32_bf16 v[122:125], v[156:159], v[182:185], 0
	v_mfma_f32_16x16x32_bf16 v[122:125], v[160:163], v[186:189], v[122:125]
	s_waitcnt lgkmcnt(3)
	v_mfma_f32_16x16x32_bf16 v[106:109], v[156:159], v[190:193], 0
	v_mfma_f32_16x16x32_bf16 v[106:109], v[160:163], v[194:197], v[106:109]
	s_waitcnt lgkmcnt(1)
	v_mfma_f32_16x16x32_bf16 v[110:113], v[148:151], v[190:193], 0
	v_mfma_f32_16x16x32_bf16 v[110:113], v[152:155], v[194:197], v[110:113]
	v_mfma_f32_16x16x32_bf16 v[94:97], v[148:151], v[198:201], 0
	v_mfma_f32_16x16x32_bf16 v[94:97], v[152:155], v[202:205], v[94:97]
	v_mfma_f32_16x16x32_bf16 v[90:93], v[156:159], v[198:201], 0
	v_mfma_f32_16x16x32_bf16 v[90:93], v[160:163], v[202:205], v[90:93]
	v_mfma_f32_16x16x32_bf16 v[74:77], v[156:159], v[206:209], 0
	v_mfma_f32_16x16x32_bf16 v[74:77], v[160:163], v[210:213], v[74:77]
	s_waitcnt lgkmcnt(0)
	v_mfma_f32_16x16x32_bf16 v[78:81], v[148:151], v[206:209], 0
	v_mfma_f32_16x16x32_bf16 v[78:81], v[152:155], v[210:213], v[78:81]
	s_setprio 0
	s_setprio 1
	v_mfma_f32_16x16x32_bf16 v[118:121], v[164:167], v[182:185], 0
	v_mfma_f32_16x16x32_bf16 v[118:121], v[168:171], v[186:189], v[118:121]
	v_mfma_f32_16x16x32_bf16 v[114:117], v[172:175], v[182:185], 0
	v_mfma_f32_16x16x32_bf16 v[114:117], v[176:179], v[186:189], v[114:117]
	v_mfma_f32_16x16x32_bf16 v[98:101], v[172:175], v[190:193], 0
	v_mfma_f32_16x16x32_bf16 v[98:101], v[176:179], v[194:197], v[98:101]
	v_mfma_f32_16x16x32_bf16 v[102:105], v[164:167], v[190:193], 0
	v_mfma_f32_16x16x32_bf16 v[102:105], v[168:171], v[194:197], v[102:105]
	v_mfma_f32_16x16x32_bf16 v[86:89], v[164:167], v[198:201], 0
	v_mfma_f32_16x16x32_bf16 v[86:89], v[168:171], v[202:205], v[86:89]
	v_mfma_f32_16x16x32_bf16 v[82:85], v[172:175], v[198:201], 0
	v_mfma_f32_16x16x32_bf16 v[82:85], v[176:179], v[202:205], v[82:85]
	v_mfma_f32_16x16x32_bf16 v[66:69], v[172:175], v[206:209], 0
	v_mfma_f32_16x16x32_bf16 v[66:69], v[176:179], v[210:213], v[66:69]
	s_setprio 2
	s_barrier
	v_mfma_f32_16x16x32_bf16 v[70:73], v[164:167], v[206:209], 0
	v_mfma_f32_16x16x32_bf16 v[70:73], v[168:171], v[210:213], v[70:73]
	s_setprio 0
	ds_read_b128 v[182:185], v145 offset:16384
	ds_read_b128 v[186:189], v145 offset:17408
	ds_read_b128 v[190:193], v145 offset:18432
	ds_read_b128 v[194:197], v145 offset:19456
	ds_read_b128 v[198:201], v145 offset:20480
	ds_read_b128 v[202:205], v145 offset:21504
	ds_read_b128 v[206:209], v145 offset:22528
	ds_read_b128 v[210:213], v145 offset:23552
	s_mov_b32 s78, m0
	s_mov_b32 m0, s35
	s_nop 0
	global_load_lds_dwordx4 v139, s[20:21]
	s_mov_b32 m0, s78
	s_nop 0
	s_mov_b32 s78, m0
	s_mov_b32 m0, s36
	s_nop 0
	global_load_lds_dwordx4 v141, s[20:21]
	s_mov_b32 m0, s78
	s_add_u32 s78, s20, 0x80000
	s_addc_u32 s79, s21, 0
	s_mov_b32 s80, m0
	s_mov_b32 m0, s37
	s_nop 0
	global_load_lds_dwordx4 v139, s[78:79]
	s_mov_b32 m0, s80
	s_nop 0
	s_mov_b32 s80, m0
	s_mov_b32 m0, s40
	s_nop 0
	global_load_lds_dwordx4 v141, s[78:79]
	s_mov_b32 m0, s80
	s_waitcnt vmcnt(4)
	s_waitcnt lgkmcnt(0)
	s_barrier
	s_setprio 1
	s_waitcnt lgkmcnt(7)
	v_mfma_f32_16x16x32_bf16 v[62:65], v[148:151], v[182:185], 0
	v_mfma_f32_16x16x32_bf16 v[62:65], v[152:155], v[186:189], v[62:65]
	s_waitcnt lgkmcnt(5)
	v_mfma_f32_16x16x32_bf16 v[58:61], v[156:159], v[182:185], 0
	v_mfma_f32_16x16x32_bf16 v[58:61], v[160:163], v[186:189], v[58:61]
	s_waitcnt lgkmcnt(3)
	v_mfma_f32_16x16x32_bf16 v[42:45], v[156:159], v[190:193], 0
	v_mfma_f32_16x16x32_bf16 v[42:45], v[160:163], v[194:197], v[42:45]
	s_waitcnt lgkmcnt(1)
	v_mfma_f32_16x16x32_bf16 v[46:49], v[148:151], v[190:193], 0
	v_mfma_f32_16x16x32_bf16 v[46:49], v[152:155], v[194:197], v[46:49]
	v_mfma_f32_16x16x32_bf16 v[30:33], v[148:151], v[198:201], 0
	v_mfma_f32_16x16x32_bf16 v[30:33], v[152:155], v[202:205], v[30:33]
	v_mfma_f32_16x16x32_bf16 v[26:29], v[156:159], v[198:201], 0
	v_mfma_f32_16x16x32_bf16 v[26:29], v[160:163], v[202:205], v[26:29]
	v_mfma_f32_16x16x32_bf16 v[10:13], v[156:159], v[206:209], 0
	v_mfma_f32_16x16x32_bf16 v[10:13], v[160:163], v[210:213], v[10:13]
	s_waitcnt lgkmcnt(0)
	v_mfma_f32_16x16x32_bf16 v[14:17], v[148:151], v[206:209], 0
	v_mfma_f32_16x16x32_bf16 v[14:17], v[152:155], v[210:213], v[14:17]
	s_setprio 0
	s_setprio 1
	v_mfma_f32_16x16x32_bf16 v[54:57], v[164:167], v[182:185], 0
	v_mfma_f32_16x16x32_bf16 v[54:57], v[168:171], v[186:189], v[54:57]
	v_mfma_f32_16x16x32_bf16 v[50:53], v[172:175], v[182:185], 0
	v_mfma_f32_16x16x32_bf16 v[50:53], v[176:179], v[186:189], v[50:53]
	v_mfma_f32_16x16x32_bf16 v[34:37], v[172:175], v[190:193], 0
	v_mfma_f32_16x16x32_bf16 v[34:37], v[176:179], v[194:197], v[34:37]
	v_mfma_f32_16x16x32_bf16 v[38:41], v[164:167], v[190:193], 0
	v_mfma_f32_16x16x32_bf16 v[38:41], v[168:171], v[194:197], v[38:41]
	v_mfma_f32_16x16x32_bf16 v[22:25], v[164:167], v[198:201], 0
	v_mfma_f32_16x16x32_bf16 v[22:25], v[168:171], v[202:205], v[22:25]
	v_mfma_f32_16x16x32_bf16 v[18:21], v[172:175], v[198:201], 0
	v_mfma_f32_16x16x32_bf16 v[18:21], v[176:179], v[202:205], v[18:21]
	v_mfma_f32_16x16x32_bf16 v[2:5], v[172:175], v[206:209], 0
	v_mfma_f32_16x16x32_bf16 v[2:5], v[176:179], v[210:213], v[2:5]
	s_setprio 2
	s_barrier
	v_mfma_f32_16x16x32_bf16 v[6:9], v[164:167], v[206:209], 0
	v_mfma_f32_16x16x32_bf16 v[6:9], v[168:171], v[210:213], v[6:9]
	s_setprio 0
	ds_read_b128 v[148:151], v146
	ds_read_b128 v[152:155], v146 offset:1024
	ds_read_b128 v[156:159], v146 offset:2048
	ds_read_b128 v[160:163], v146 offset:3072
	ds_read_b128 v[164:167], v147
	ds_read_b128 v[168:171], v147 offset:1024
	ds_read_b128 v[172:175], v147 offset:2048
	ds_read_b128 v[176:179], v147 offset:3072
	ds_read_b128 v[182:185], v145 offset:32768
	ds_read_b128 v[186:189], v145 offset:33792
	ds_read_b128 v[190:193], v145 offset:34816
	ds_read_b128 v[194:197], v145 offset:35840
	ds_read_b128 v[198:201], v145 offset:36864
	ds_read_b128 v[202:205], v145 offset:37888
	ds_read_b128 v[206:209], v145 offset:38912
	ds_read_b128 v[210:213], v145 offset:39936
	s_mov_b32 s78, m0
	s_mov_b32 m0, s31
	s_nop 0
	global_load_lds_dwordx4 v138, s[22:23]
	s_mov_b32 m0, s78
	s_nop 0
	s_mov_b32 s78, m0
	s_mov_b32 m0, s41
	s_nop 0
	global_load_lds_dwordx4 v140, s[22:23]
	s_mov_b32 m0, s78
	s_add_u32 s22, s22, 0x80000
	s_addc_u32 s23, s23, 0
	s_mov_b32 s78, m0
	s_mov_b32 m0, s42
	s_nop 0
	global_load_lds_dwordx4 v138, s[22:23]
	s_mov_b32 m0, s78
	s_nop 0
	s_mov_b32 s78, m0
	s_mov_b32 m0, s43
	s_nop 0
	global_load_lds_dwordx4 v140, s[22:23]
	s_mov_b32 m0, s78
	s_waitcnt vmcnt(8)
	s_waitcnt lgkmcnt(0)
	s_barrier
	s_setprio 1
	s_waitcnt lgkmcnt(7)
	v_mfma_f32_16x16x32_bf16 v[126:129], v[148:151], v[182:185], v[126:129]
	v_mfma_f32_16x16x32_bf16 v[126:129], v[152:155], v[186:189], v[126:129]
	s_waitcnt lgkmcnt(5)
	v_mfma_f32_16x16x32_bf16 v[122:125], v[156:159], v[182:185], v[122:125]
	v_mfma_f32_16x16x32_bf16 v[122:125], v[160:163], v[186:189], v[122:125]
	s_waitcnt lgkmcnt(3)
	v_mfma_f32_16x16x32_bf16 v[106:109], v[156:159], v[190:193], v[106:109]
	v_mfma_f32_16x16x32_bf16 v[106:109], v[160:163], v[194:197], v[106:109]
	s_waitcnt lgkmcnt(1)
	v_mfma_f32_16x16x32_bf16 v[110:113], v[148:151], v[190:193], v[110:113]
	v_mfma_f32_16x16x32_bf16 v[110:113], v[152:155], v[194:197], v[110:113]
	v_mfma_f32_16x16x32_bf16 v[94:97], v[148:151], v[198:201], v[94:97]
	v_mfma_f32_16x16x32_bf16 v[94:97], v[152:155], v[202:205], v[94:97]
	v_mfma_f32_16x16x32_bf16 v[90:93], v[156:159], v[198:201], v[90:93]
	v_mfma_f32_16x16x32_bf16 v[90:93], v[160:163], v[202:205], v[90:93]
	v_mfma_f32_16x16x32_bf16 v[74:77], v[156:159], v[206:209], v[74:77]
	v_mfma_f32_16x16x32_bf16 v[74:77], v[160:163], v[210:213], v[74:77]
	s_waitcnt lgkmcnt(0)
	v_mfma_f32_16x16x32_bf16 v[78:81], v[148:151], v[206:209], v[78:81]
	v_mfma_f32_16x16x32_bf16 v[78:81], v[152:155], v[210:213], v[78:81]
	s_setprio 0
	s_setprio 1
	v_mfma_f32_16x16x32_bf16 v[118:121], v[164:167], v[182:185], v[118:121]
	v_mfma_f32_16x16x32_bf16 v[118:121], v[168:171], v[186:189], v[118:121]
	v_mfma_f32_16x16x32_bf16 v[114:117], v[172:175], v[182:185], v[114:117]
	v_mfma_f32_16x16x32_bf16 v[114:117], v[176:179], v[186:189], v[114:117]
	v_mfma_f32_16x16x32_bf16 v[98:101], v[172:175], v[190:193], v[98:101]
	v_mfma_f32_16x16x32_bf16 v[98:101], v[176:179], v[194:197], v[98:101]
	v_mfma_f32_16x16x32_bf16 v[102:105], v[164:167], v[190:193], v[102:105]
	v_mfma_f32_16x16x32_bf16 v[102:105], v[168:171], v[194:197], v[102:105]
	v_mfma_f32_16x16x32_bf16 v[86:89], v[164:167], v[198:201], v[86:89]
	v_mfma_f32_16x16x32_bf16 v[86:89], v[168:171], v[202:205], v[86:89]
	v_mfma_f32_16x16x32_bf16 v[82:85], v[172:175], v[198:201], v[82:85]
	v_mfma_f32_16x16x32_bf16 v[82:85], v[176:179], v[202:205], v[82:85]
	v_mfma_f32_16x16x32_bf16 v[66:69], v[172:175], v[206:209], v[66:69]
	v_mfma_f32_16x16x32_bf16 v[66:69], v[176:179], v[210:213], v[66:69]
	s_setprio 2
	s_barrier
	v_mfma_f32_16x16x32_bf16 v[70:73], v[164:167], v[206:209], v[70:73]
	v_mfma_f32_16x16x32_bf16 v[70:73], v[168:171], v[210:213], v[70:73]
	s_setprio 0
	ds_read_b128 v[182:185], v145 offset:49152
	ds_read_b128 v[186:189], v145 offset:50176
	ds_read_b128 v[190:193], v145 offset:51200
	ds_read_b128 v[194:197], v145 offset:52224
	ds_read_b128 v[198:201], v145 offset:53248
	ds_read_b128 v[202:205], v145 offset:54272
	ds_read_b128 v[206:209], v145 offset:55296
	ds_read_b128 v[210:213], v145 offset:56320
	s_add_u32 s22, s20, 0x80
	s_addc_u32 s23, s21, 0
	s_mov_b32 s78, m0
	s_mov_b32 m0, s46
	s_nop 0
	global_load_lds_dwordx4 v139, s[22:23]
	s_mov_b32 m0, s78
	s_add_u32 s20, s20, 0x80080
	s_mov_b32 s78, m0
	s_mov_b32 m0, s47
	s_nop 0
	global_load_lds_dwordx4 v141, s[22:23]
	s_mov_b32 m0, s78
	s_addc_u32 s21, s21, 0
	s_mov_b32 s22, m0
	s_mov_b32 m0, s48
	s_nop 0
	global_load_lds_dwordx4 v139, s[20:21]
	s_mov_b32 m0, s22
	s_nop 0
	s_mov_b32 s22, m0
	s_mov_b32 m0, s49
	s_nop 0
	global_load_lds_dwordx4 v141, s[20:21]
	s_mov_b32 m0, s22
	s_waitcnt vmcnt(4)
	s_waitcnt lgkmcnt(0)
	s_barrier
	s_setprio 1
	s_waitcnt lgkmcnt(7)
	v_mfma_f32_16x16x32_bf16 v[62:65], v[148:151], v[182:185], v[62:65]
	v_mfma_f32_16x16x32_bf16 v[62:65], v[152:155], v[186:189], v[62:65]
	s_waitcnt lgkmcnt(5)
	v_mfma_f32_16x16x32_bf16 v[58:61], v[156:159], v[182:185], v[58:61]
	v_mfma_f32_16x16x32_bf16 v[58:61], v[160:163], v[186:189], v[58:61]
	s_waitcnt lgkmcnt(3)
	v_mfma_f32_16x16x32_bf16 v[42:45], v[156:159], v[190:193], v[42:45]
	v_mfma_f32_16x16x32_bf16 v[42:45], v[160:163], v[194:197], v[42:45]
	s_waitcnt lgkmcnt(1)
	v_mfma_f32_16x16x32_bf16 v[46:49], v[148:151], v[190:193], v[46:49]
	v_mfma_f32_16x16x32_bf16 v[46:49], v[152:155], v[194:197], v[46:49]
	v_mfma_f32_16x16x32_bf16 v[30:33], v[148:151], v[198:201], v[30:33]
	v_mfma_f32_16x16x32_bf16 v[30:33], v[152:155], v[202:205], v[30:33]
	v_mfma_f32_16x16x32_bf16 v[26:29], v[156:159], v[198:201], v[26:29]
	v_mfma_f32_16x16x32_bf16 v[26:29], v[160:163], v[202:205], v[26:29]
	v_mfma_f32_16x16x32_bf16 v[10:13], v[156:159], v[206:209], v[10:13]
	v_mfma_f32_16x16x32_bf16 v[10:13], v[160:163], v[210:213], v[10:13]
	s_waitcnt lgkmcnt(0)
	v_mfma_f32_16x16x32_bf16 v[14:17], v[148:151], v[206:209], v[14:17]
	v_mfma_f32_16x16x32_bf16 v[14:17], v[152:155], v[210:213], v[14:17]
	s_setprio 0
	s_setprio 1
	v_mfma_f32_16x16x32_bf16 v[54:57], v[164:167], v[182:185], v[54:57]
	v_mfma_f32_16x16x32_bf16 v[54:57], v[168:171], v[186:189], v[54:57]
	v_mfma_f32_16x16x32_bf16 v[50:53], v[172:175], v[182:185], v[50:53]
	v_mfma_f32_16x16x32_bf16 v[50:53], v[176:179], v[186:189], v[50:53]
	v_mfma_f32_16x16x32_bf16 v[34:37], v[172:175], v[190:193], v[34:37]
	v_mfma_f32_16x16x32_bf16 v[34:37], v[176:179], v[194:197], v[34:37]
	v_mfma_f32_16x16x32_bf16 v[38:41], v[164:167], v[190:193], v[38:41]
	v_mfma_f32_16x16x32_bf16 v[38:41], v[168:171], v[194:197], v[38:41]
	v_mfma_f32_16x16x32_bf16 v[22:25], v[164:167], v[198:201], v[22:25]
	v_mfma_f32_16x16x32_bf16 v[22:25], v[168:171], v[202:205], v[22:25]
	v_mfma_f32_16x16x32_bf16 v[18:21], v[172:175], v[198:201], v[18:21]
	v_mfma_f32_16x16x32_bf16 v[18:21], v[176:179], v[202:205], v[18:21]
	v_mfma_f32_16x16x32_bf16 v[2:5], v[172:175], v[206:209], v[2:5]
	v_mfma_f32_16x16x32_bf16 v[2:5], v[176:179], v[210:213], v[2:5]
	s_setprio 2
	s_barrier
	v_mfma_f32_16x16x32_bf16 v[6:9], v[164:167], v[206:209], v[6:9]
	v_mfma_f32_16x16x32_bf16 v[6:9], v[168:171], v[210:213], v[6:9]
	s_setprio 0
	s_add_i32 s77, s77, 2
	s_add_u32 s73, s73, 0x100
	s_addc_u32 s74, s74, 0
	s_add_u32 s18, s18, 0x100
	s_addc_u32 s19, s19, 0
	s_add_u32 s75, s75, 0x100
	s_addc_u32 s76, s76, 0
	s_cmp_gt_u32 s77, 29
	.p2align 6
.LBB0_1224:
	ds_read_b128 v[148:151], v143
	ds_read_b128 v[152:155], v143 offset:1024
	ds_read_b128 v[156:159], v143 offset:2048
	ds_read_b128 v[160:163], v143 offset:3072
	ds_read_b128 v[164:167], v144
	ds_read_b128 v[168:171], v144 offset:1024
	ds_read_b128 v[172:175], v144 offset:2048
	ds_read_b128 v[176:179], v144 offset:3072
	s_cmp_eq_u32 s77, 28
	s_cselect_b32 s21, s9, s74
	s_cselect_b32 s20, s67, s73
	s_cselect_b32 s23, s11, s76
	s_cselect_b32 s22, s66, s75
	ds_read_b128 v[182:185], v145
	ds_read_b128 v[186:189], v145 offset:1024
	ds_read_b128 v[190:193], v145 offset:2048
	ds_read_b128 v[194:197], v145 offset:3072
	ds_read_b128 v[198:201], v145 offset:4096
	ds_read_b128 v[202:205], v145 offset:5120
	ds_read_b128 v[206:209], v145 offset:6144
	ds_read_b128 v[210:213], v145 offset:7168
	s_add_u32 s78, s18, 0xfff80000
	s_addc_u32 s79, s19, -1
	s_mov_b32 s80, m0
	s_mov_b32 m0, s56
	s_nop 0
	global_load_lds_dwordx4 v138, s[78:79]
	s_mov_b32 m0, s80
	s_nop 0
	s_mov_b32 s80, m0
	s_mov_b32 m0, s59
	s_nop 0
	global_load_lds_dwordx4 v140, s[78:79]
	s_mov_b32 m0, s80
	s_mov_b32 s78, m0
	s_mov_b32 m0, s57
	s_nop 0
	global_load_lds_dwordx4 v138, s[18:19]
	s_mov_b32 m0, s78
	s_nop 0
	s_mov_b32 s78, m0
	s_mov_b32 m0, s64
	s_nop 0
	global_load_lds_dwordx4 v140, s[18:19]
	s_mov_b32 m0, s78
	s_waitcnt vmcnt(8)
	s_waitcnt lgkmcnt(0)
	s_barrier
	s_setprio 1
	s_waitcnt lgkmcnt(7)
	v_mfma_f32_16x16x32_bf16 v[126:129], v[148:151], v[182:185], v[126:129]
	v_mfma_f32_16x16x32_bf16 v[126:129], v[152:155], v[186:189], v[126:129]
	s_waitcnt lgkmcnt(5)
	v_mfma_f32_16x16x32_bf16 v[122:125], v[156:159], v[182:185], v[122:125]
	v_mfma_f32_16x16x32_bf16 v[122:125], v[160:163], v[186:189], v[122:125]
	s_waitcnt lgkmcnt(3)
	v_mfma_f32_16x16x32_bf16 v[106:109], v[156:159], v[190:193], v[106:109]
	v_mfma_f32_16x16x32_bf16 v[106:109], v[160:163], v[194:197], v[106:109]
	s_waitcnt lgkmcnt(1)
	v_mfma_f32_16x16x32_bf16 v[110:113], v[148:151], v[190:193], v[110:113]
	v_mfma_f32_16x16x32_bf16 v[110:113], v[152:155], v[194:197], v[110:113]
	v_mfma_f32_16x16x32_bf16 v[94:97], v[148:151], v[198:201], v[94:97]
	v_mfma_f32_16x16x32_bf16 v[94:97], v[152:155], v[202:205], v[94:97]
	v_mfma_f32_16x16x32_bf16 v[90:93], v[156:159], v[198:201], v[90:93]
	v_mfma_f32_16x16x32_bf16 v[90:93], v[160:163], v[202:205], v[90:93]
	v_mfma_f32_16x16x32_bf16 v[74:77], v[156:159], v[206:209], v[74:77]
	v_mfma_f32_16x16x32_bf16 v[74:77], v[160:163], v[210:213], v[74:77]
	s_waitcnt lgkmcnt(0)
	v_mfma_f32_16x16x32_bf16 v[78:81], v[148:151], v[206:209], v[78:81]
	v_mfma_f32_16x16x32_bf16 v[78:81], v[152:155], v[210:213], v[78:81]
	s_setprio 0
	s_setprio 1
	v_mfma_f32_16x16x32_bf16 v[118:121], v[164:167], v[182:185], v[118:121]
	v_mfma_f32_16x16x32_bf16 v[118:121], v[168:171], v[186:189], v[118:121]
	v_mfma_f32_16x16x32_bf16 v[114:117], v[172:175], v[182:185], v[114:117]
	v_mfma_f32_16x16x32_bf16 v[114:117], v[176:179], v[186:189], v[114:117]
	v_mfma_f32_16x16x32_bf16 v[98:101], v[172:175], v[190:193], v[98:101]
	v_mfma_f32_16x16x32_bf16 v[98:101], v[176:179], v[194:197], v[98:101]
	v_mfma_f32_16x16x32_bf16 v[102:105], v[164:167], v[190:193], v[102:105]
	v_mfma_f32_16x16x32_bf16 v[102:105], v[168:171], v[194:197], v[102:105]
	v_mfma_f32_16x16x32_bf16 v[86:89], v[164:167], v[198:201], v[86:89]
	v_mfma_f32_16x16x32_bf16 v[86:89], v[168:171], v[202:205], v[86:89]
	v_mfma_f32_16x16x32_bf16 v[82:85], v[172:175], v[198:201], v[82:85]
	v_mfma_f32_16x16x32_bf16 v[82:85], v[176:179], v[202:205], v[82:85]
	v_mfma_f32_16x16x32_bf16 v[66:69], v[172:175], v[206:209], v[66:69]
	v_mfma_f32_16x16x32_bf16 v[66:69], v[176:179], v[210:213], v[66:69]
	s_setprio 2
	s_barrier
	v_mfma_f32_16x16x32_bf16 v[70:73], v[164:167], v[206:209], v[70:73]
	v_mfma_f32_16x16x32_bf16 v[70:73], v[168:171], v[210:213], v[70:73]
	s_setprio 0
	ds_read_b128 v[182:185], v145 offset:16384
	ds_read_b128 v[186:189], v145 offset:17408
	ds_read_b128 v[190:193], v145 offset:18432
	ds_read_b128 v[194:197], v145 offset:19456
	ds_read_b128 v[198:201], v145 offset:20480
	ds_read_b128 v[202:205], v145 offset:21504
	ds_read_b128 v[206:209], v145 offset:22528
	ds_read_b128 v[210:213], v145 offset:23552
	s_mov_b32 s78, m0
	s_mov_b32 m0, s35
	s_nop 0
	global_load_lds_dwordx4 v139, s[20:21]
	s_mov_b32 m0, s78
	s_nop 0
	s_mov_b32 s78, m0
	s_mov_b32 m0, s36
	s_nop 0
	global_load_lds_dwordx4 v141, s[20:21]
	s_mov_b32 m0, s78
	s_add_u32 s78, s20, 0x80000
	s_addc_u32 s79, s21, 0
	s_mov_b32 s80, m0
	s_mov_b32 m0, s37
	s_nop 0
	global_load_lds_dwordx4 v139, s[78:79]
	s_mov_b32 m0, s80
	s_nop 0
	s_mov_b32 s80, m0
	s_mov_b32 m0, s40
	s_nop 0
	global_load_lds_dwordx4 v141, s[78:79]
	s_mov_b32 m0, s80
	s_waitcnt vmcnt(4)
	s_waitcnt lgkmcnt(0)
	s_barrier
	s_setprio 1
	s_waitcnt lgkmcnt(7)
	v_mfma_f32_16x16x32_bf16 v[62:65], v[148:151], v[182:185], v[62:65]
	v_mfma_f32_16x16x32_bf16 v[62:65], v[152:155], v[186:189], v[62:65]
	s_waitcnt lgkmcnt(5)
	v_mfma_f32_16x16x32_bf16 v[58:61], v[156:159], v[182:185], v[58:61]
	v_mfma_f32_16x16x32_bf16 v[58:61], v[160:163], v[186:189], v[58:61]
	s_waitcnt lgkmcnt(3)
	v_mfma_f32_16x16x32_bf16 v[42:45], v[156:159], v[190:193], v[42:45]
	v_mfma_f32_16x16x32_bf16 v[42:45], v[160:163], v[194:197], v[42:45]
	s_waitcnt lgkmcnt(1)
	v_mfma_f32_16x16x32_bf16 v[46:49], v[148:151], v[190:193], v[46:49]
	v_mfma_f32_16x16x32_bf16 v[46:49], v[152:155], v[194:197], v[46:49]
	v_mfma_f32_16x16x32_bf16 v[30:33], v[148:151], v[198:201], v[30:33]
	v_mfma_f32_16x16x32_bf16 v[30:33], v[152:155], v[202:205], v[30:33]
	v_mfma_f32_16x16x32_bf16 v[26:29], v[156:159], v[198:201], v[26:29]
	v_mfma_f32_16x16x32_bf16 v[26:29], v[160:163], v[202:205], v[26:29]
	v_mfma_f32_16x16x32_bf16 v[10:13], v[156:159], v[206:209], v[10:13]
	v_mfma_f32_16x16x32_bf16 v[10:13], v[160:163], v[210:213], v[10:13]
	s_waitcnt lgkmcnt(0)
	v_mfma_f32_16x16x32_bf16 v[14:17], v[148:151], v[206:209], v[14:17]
	v_mfma_f32_16x16x32_bf16 v[14:17], v[152:155], v[210:213], v[14:17]
	s_setprio 0
	s_setprio 1
	v_mfma_f32_16x16x32_bf16 v[54:57], v[164:167], v[182:185], v[54:57]
	v_mfma_f32_16x16x32_bf16 v[54:57], v[168:171], v[186:189], v[54:57]
	v_mfma_f32_16x16x32_bf16 v[50:53], v[172:175], v[182:185], v[50:53]
	v_mfma_f32_16x16x32_bf16 v[50:53], v[176:179], v[186:189], v[50:53]
	v_mfma_f32_16x16x32_bf16 v[34:37], v[172:175], v[190:193], v[34:37]
	v_mfma_f32_16x16x32_bf16 v[34:37], v[176:179], v[194:197], v[34:37]
	v_mfma_f32_16x16x32_bf16 v[38:41], v[164:167], v[190:193], v[38:41]
	v_mfma_f32_16x16x32_bf16 v[38:41], v[168:171], v[194:197], v[38:41]
	v_mfma_f32_16x16x32_bf16 v[22:25], v[164:167], v[198:201], v[22:25]
	v_mfma_f32_16x16x32_bf16 v[22:25], v[168:171], v[202:205], v[22:25]
	v_mfma_f32_16x16x32_bf16 v[18:21], v[172:175], v[198:201], v[18:21]
	v_mfma_f32_16x16x32_bf16 v[18:21], v[176:179], v[202:205], v[18:21]
	v_mfma_f32_16x16x32_bf16 v[2:5], v[172:175], v[206:209], v[2:5]
	v_mfma_f32_16x16x32_bf16 v[2:5], v[176:179], v[210:213], v[2:5]
	s_setprio 2
	s_barrier
	v_mfma_f32_16x16x32_bf16 v[6:9], v[164:167], v[206:209], v[6:9]
	v_mfma_f32_16x16x32_bf16 v[6:9], v[168:171], v[210:213], v[6:9]
	s_setprio 0
	ds_read_b128 v[148:151], v146
	ds_read_b128 v[152:155], v146 offset:1024
	ds_read_b128 v[156:159], v146 offset:2048
	ds_read_b128 v[160:163], v146 offset:3072
	ds_read_b128 v[164:167], v147
	ds_read_b128 v[168:171], v147 offset:1024
	ds_read_b128 v[172:175], v147 offset:2048
	ds_read_b128 v[176:179], v147 offset:3072
	ds_read_b128 v[182:185], v145 offset:32768
	ds_read_b128 v[186:189], v145 offset:33792
	ds_read_b128 v[190:193], v145 offset:34816
	ds_read_b128 v[194:197], v145 offset:35840
	ds_read_b128 v[198:201], v145 offset:36864
	ds_read_b128 v[202:205], v145 offset:37888
	ds_read_b128 v[206:209], v145 offset:38912
	ds_read_b128 v[210:213], v145 offset:39936
	s_mov_b32 s78, m0
	s_mov_b32 m0, s31
	s_nop 0
	global_load_lds_dwordx4 v138, s[22:23]
	s_mov_b32 m0, s78
	s_nop 0
	s_mov_b32 s78, m0
	s_mov_b32 m0, s41
	s_nop 0
	global_load_lds_dwordx4 v140, s[22:23]
	s_mov_b32 m0, s78
	s_add_u32 s22, s22, 0x80000
	s_addc_u32 s23, s23, 0
	s_mov_b32 s78, m0
	s_mov_b32 m0, s42
	s_nop 0
	global_load_lds_dwordx4 v138, s[22:23]
	s_mov_b32 m0, s78
	s_nop 0
	s_mov_b32 s78, m0
	s_mov_b32 m0, s43
	s_nop 0
	global_load_lds_dwordx4 v140, s[22:23]
	s_mov_b32 m0, s78
	s_waitcnt vmcnt(8)
	s_waitcnt lgkmcnt(0)
	s_barrier
	s_setprio 1
	s_waitcnt lgkmcnt(7)
	v_mfma_f32_16x16x32_bf16 v[126:129], v[148:151], v[182:185], v[126:129]
	v_mfma_f32_16x16x32_bf16 v[126:129], v[152:155], v[186:189], v[126:129]
	s_waitcnt lgkmcnt(5)
	v_mfma_f32_16x16x32_bf16 v[122:125], v[156:159], v[182:185], v[122:125]
	v_mfma_f32_16x16x32_bf16 v[122:125], v[160:163], v[186:189], v[122:125]
	s_waitcnt lgkmcnt(3)
	v_mfma_f32_16x16x32_bf16 v[106:109], v[156:159], v[190:193], v[106:109]
	v_mfma_f32_16x16x32_bf16 v[106:109], v[160:163], v[194:197], v[106:109]
	s_waitcnt lgkmcnt(1)
	v_mfma_f32_16x16x32_bf16 v[110:113], v[148:151], v[190:193], v[110:113]
	v_mfma_f32_16x16x32_bf16 v[110:113], v[152:155], v[194:197], v[110:113]
	v_mfma_f32_16x16x32_bf16 v[94:97], v[148:151], v[198:201], v[94:97]
	v_mfma_f32_16x16x32_bf16 v[94:97], v[152:155], v[202:205], v[94:97]
	v_mfma_f32_16x16x32_bf16 v[90:93], v[156:159], v[198:201], v[90:93]
	v_mfma_f32_16x16x32_bf16 v[90:93], v[160:163], v[202:205], v[90:93]
	v_mfma_f32_16x16x32_bf16 v[74:77], v[156:159], v[206:209], v[74:77]
	v_mfma_f32_16x16x32_bf16 v[74:77], v[160:163], v[210:213], v[74:77]
	s_waitcnt lgkmcnt(0)
	v_mfma_f32_16x16x32_bf16 v[78:81], v[148:151], v[206:209], v[78:81]
	v_mfma_f32_16x16x32_bf16 v[78:81], v[152:155], v[210:213], v[78:81]
	s_setprio 0
	s_setprio 1
	v_mfma_f32_16x16x32_bf16 v[118:121], v[164:167], v[182:185], v[118:121]
	v_mfma_f32_16x16x32_bf16 v[118:121], v[168:171], v[186:189], v[118:121]
	v_mfma_f32_16x16x32_bf16 v[114:117], v[172:175], v[182:185], v[114:117]
	v_mfma_f32_16x16x32_bf16 v[114:117], v[176:179], v[186:189], v[114:117]
	v_mfma_f32_16x16x32_bf16 v[98:101], v[172:175], v[190:193], v[98:101]
	v_mfma_f32_16x16x32_bf16 v[98:101], v[176:179], v[194:197], v[98:101]
	v_mfma_f32_16x16x32_bf16 v[102:105], v[164:167], v[190:193], v[102:105]
	v_mfma_f32_16x16x32_bf16 v[102:105], v[168:171], v[194:197], v[102:105]
	v_mfma_f32_16x16x32_bf16 v[86:89], v[164:167], v[198:201], v[86:89]
	v_mfma_f32_16x16x32_bf16 v[86:89], v[168:171], v[202:205], v[86:89]
	v_mfma_f32_16x16x32_bf16 v[82:85], v[172:175], v[198:201], v[82:85]
	v_mfma_f32_16x16x32_bf16 v[82:85], v[176:179], v[202:205], v[82:85]
	v_mfma_f32_16x16x32_bf16 v[66:69], v[172:175], v[206:209], v[66:69]
	v_mfma_f32_16x16x32_bf16 v[66:69], v[176:179], v[210:213], v[66:69]
	s_setprio 2
	s_barrier
	v_mfma_f32_16x16x32_bf16 v[70:73], v[164:167], v[206:209], v[70:73]
	v_mfma_f32_16x16x32_bf16 v[70:73], v[168:171], v[210:213], v[70:73]
	s_setprio 0
	ds_read_b128 v[182:185], v145 offset:49152
	ds_read_b128 v[186:189], v145 offset:50176
	ds_read_b128 v[190:193], v145 offset:51200
	ds_read_b128 v[194:197], v145 offset:52224
	ds_read_b128 v[198:201], v145 offset:53248
	ds_read_b128 v[202:205], v145 offset:54272
	ds_read_b128 v[206:209], v145 offset:55296
	ds_read_b128 v[210:213], v145 offset:56320
	s_add_u32 s22, s20, 0x80
	s_addc_u32 s23, s21, 0
	s_mov_b32 s78, m0
	s_mov_b32 m0, s46
	s_nop 0
	global_load_lds_dwordx4 v139, s[22:23]
	s_mov_b32 m0, s78
	s_add_u32 s20, s20, 0x80080
	s_mov_b32 s78, m0
	s_mov_b32 m0, s47
	s_nop 0
	global_load_lds_dwordx4 v141, s[22:23]
	s_mov_b32 m0, s78
	s_addc_u32 s21, s21, 0
	s_mov_b32 s22, m0
	s_mov_b32 m0, s48
	s_nop 0
	global_load_lds_dwordx4 v139, s[20:21]
	s_mov_b32 m0, s22
	s_nop 0
	s_mov_b32 s22, m0
	s_mov_b32 m0, s49
	s_nop 0
	global_load_lds_dwordx4 v141, s[20:21]
	s_mov_b32 m0, s22
	s_waitcnt vmcnt(4)
	s_waitcnt lgkmcnt(0)
	s_barrier
	s_setprio 1
	s_waitcnt lgkmcnt(7)
	v_mfma_f32_16x16x32_bf16 v[62:65], v[148:151], v[182:185], v[62:65]
	v_mfma_f32_16x16x32_bf16 v[62:65], v[152:155], v[186:189], v[62:65]
	s_waitcnt lgkmcnt(5)
	v_mfma_f32_16x16x32_bf16 v[58:61], v[156:159], v[182:185], v[58:61]
	v_mfma_f32_16x16x32_bf16 v[58:61], v[160:163], v[186:189], v[58:61]
	s_waitcnt lgkmcnt(3)
	v_mfma_f32_16x16x32_bf16 v[42:45], v[156:159], v[190:193], v[42:45]
	v_mfma_f32_16x16x32_bf16 v[42:45], v[160:163], v[194:197], v[42:45]
	s_waitcnt lgkmcnt(1)
	v_mfma_f32_16x16x32_bf16 v[46:49], v[148:151], v[190:193], v[46:49]
	v_mfma_f32_16x16x32_bf16 v[46:49], v[152:155], v[194:197], v[46:49]
	v_mfma_f32_16x16x32_bf16 v[30:33], v[148:151], v[198:201], v[30:33]
	v_mfma_f32_16x16x32_bf16 v[30:33], v[152:155], v[202:205], v[30:33]
	v_mfma_f32_16x16x32_bf16 v[26:29], v[156:159], v[198:201], v[26:29]
	v_mfma_f32_16x16x32_bf16 v[26:29], v[160:163], v[202:205], v[26:29]
	v_mfma_f32_16x16x32_bf16 v[10:13], v[156:159], v[206:209], v[10:13]
	v_mfma_f32_16x16x32_bf16 v[10:13], v[160:163], v[210:213], v[10:13]
	s_waitcnt lgkmcnt(0)
	v_mfma_f32_16x16x32_bf16 v[14:17], v[148:151], v[206:209], v[14:17]
	v_mfma_f32_16x16x32_bf16 v[14:17], v[152:155], v[210:213], v[14:17]
	s_setprio 0
	s_setprio 1
	v_mfma_f32_16x16x32_bf16 v[54:57], v[164:167], v[182:185], v[54:57]
	v_mfma_f32_16x16x32_bf16 v[54:57], v[168:171], v[186:189], v[54:57]
	v_mfma_f32_16x16x32_bf16 v[50:53], v[172:175], v[182:185], v[50:53]
	v_mfma_f32_16x16x32_bf16 v[50:53], v[176:179], v[186:189], v[50:53]
	v_mfma_f32_16x16x32_bf16 v[34:37], v[172:175], v[190:193], v[34:37]
	v_mfma_f32_16x16x32_bf16 v[34:37], v[176:179], v[194:197], v[34:37]
	v_mfma_f32_16x16x32_bf16 v[38:41], v[164:167], v[190:193], v[38:41]
	v_mfma_f32_16x16x32_bf16 v[38:41], v[168:171], v[194:197], v[38:41]
	v_mfma_f32_16x16x32_bf16 v[22:25], v[164:167], v[198:201], v[22:25]
	v_mfma_f32_16x16x32_bf16 v[22:25], v[168:171], v[202:205], v[22:25]
	v_mfma_f32_16x16x32_bf16 v[18:21], v[172:175], v[198:201], v[18:21]
	v_mfma_f32_16x16x32_bf16 v[18:21], v[176:179], v[202:205], v[18:21]
	v_mfma_f32_16x16x32_bf16 v[2:5], v[172:175], v[206:209], v[2:5]
	v_mfma_f32_16x16x32_bf16 v[2:5], v[176:179], v[210:213], v[2:5]
	s_setprio 2
	s_barrier
	v_mfma_f32_16x16x32_bf16 v[6:9], v[164:167], v[206:209], v[6:9]
	v_mfma_f32_16x16x32_bf16 v[6:9], v[168:171], v[210:213], v[6:9]
	s_setprio 0
	s_add_i32 s77, s77, 2
	s_add_u32 s73, s73, 0x100
	s_addc_u32 s74, s74, 0
	s_add_u32 s18, s18, 0x100
	s_addc_u32 s19, s19, 0
	s_add_u32 s75, s75, 0x100
	s_addc_u32 s76, s76, 0
	s_cmp_gt_u32 s77, 29
	s_cbranch_scc0 .LBB0_1224
	v_mov_b32_e32 v212, v252
	v_mov_b32_e32 v213, v253
	s_and_b64 vcc, exec, s[6:7]
	s_cbranch_vccz .LBB0_1227
	s_barrier

.LBB0_1784:
	s_ashr_i32 s11, s10, 31
	s_lshl_b64 s[12:13], s[10:11], 20
	s_add_u32 s12, s26, s12
	s_addc_u32 s13, s27, s13
	s_and_b64 s[14:15], s[2:3], exec
	s_cselect_b32 s11, s13, s21
	s_cselect_b32 s64, s12, s20
	s_ashr_i32 s9, s8, 31
	s_lshl_b64 s[14:15], s[8:9], 20
	s_add_u32 s14, s28, s14
	s_addc_u32 s15, s29, s15
	s_and_b64 s[22:23], s[2:3], exec
	s_cselect_b32 s9, s15, s19
	s_cselect_b32 s65, s14, s18
	s_add_u32 s66, s18, 0x100
	s_addc_u32 s67, s19, 0
	s_add_u32 s18, s20, 0x80080
	s_addc_u32 s19, s21, 0
	s_add_u32 s70, s20, 0x100
	s_addc_u32 s71, s21, 0
	s_mov_b32 s73, -2
	v_mov_b32_e32 v252, v212
	v_mov_b32_e32 v253, v213
	ds_read_b128 v[148:151], v143
	ds_read_b128 v[152:155], v143 offset:1024
	ds_read_b128 v[156:159], v143 offset:2048
	ds_read_b128 v[160:163], v143 offset:3072
	ds_read_b128 v[164:167], v144
	ds_read_b128 v[168:171], v144 offset:1024
	ds_read_b128 v[172:175], v144 offset:2048
	ds_read_b128 v[176:179], v144 offset:3072
	s_cmp_eq_u32 s73, 28
	s_cselect_b32 s21, s9, s67
	s_cselect_b32 s20, s65, s66
	s_cselect_b32 s23, s11, s71
	s_cselect_b32 s22, s64, s70
	ds_read_b128 v[182:185], v145
	ds_read_b128 v[186:189], v145 offset:1024
	ds_read_b128 v[190:193], v145 offset:2048
	ds_read_b128 v[194:197], v145 offset:3072
	ds_read_b128 v[198:201], v145 offset:4096
	ds_read_b128 v[202:205], v145 offset:5120
	ds_read_b128 v[206:209], v145 offset:6144
	ds_read_b128 v[210:213], v145 offset:7168
	s_add_u32 s74, s18, 0xfff80000
	s_addc_u32 s75, s19, -1
	s_mov_b32 s76, m0
	s_mov_b32 m0, s56
	s_nop 0
	global_load_lds_dwordx4 v138, s[74:75]
	s_mov_b32 m0, s76
	s_nop 0
	s_mov_b32 s76, m0
	s_mov_b32 m0, s59
	s_nop 0
	global_load_lds_dwordx4 v140, s[74:75]
	s_mov_b32 m0, s76
	s_mov_b32 s74, m0
	s_mov_b32 m0, s57
	s_nop 0
	global_load_lds_dwordx4 v138, s[18:19]
	s_mov_b32 m0, s74
	s_nop 0
	s_mov_b32 s74, m0
	s_mov_b32 m0, s62
	s_nop 0
	global_load_lds_dwordx4 v140, s[18:19]
	s_mov_b32 m0, s74
	s_waitcnt vmcnt(8)
	s_waitcnt lgkmcnt(0)
	s_barrier
	s_setprio 1
	s_waitcnt lgkmcnt(7)
	v_mfma_f32_16x16x32_bf16 v[126:129], v[148:151], v[182:185], 0
	v_mfma_f32_16x16x32_bf16 v[126:129], v[152:155], v[186:189], v[126:129]
	s_waitcnt lgkmcnt(5)
	v_mfma_f32_16x16x32_bf16 v[122:125], v[156:159], v[182:185], 0
	v_mfma_f32_16x16x32_bf16 v[122:125], v[160:163], v[186:189], v[122:125]
	s_waitcnt lgkmcnt(3)
	v_mfma_f32_16x16x32_bf16 v[106:109], v[156:159], v[190:193], 0
	v_mfma_f32_16x16x32_bf16 v[106:109], v[160:163], v[194:197], v[106:109]
	s_waitcnt lgkmcnt(1)
	v_mfma_f32_16x16x32_bf16 v[110:113], v[148:151], v[190:193], 0
	v_mfma_f32_16x16x32_bf16 v[110:113], v[152:155], v[194:197], v[110:113]
	v_mfma_f32_16x16x32_bf16 v[94:97], v[148:151], v[198:201], 0
	v_mfma_f32_16x16x32_bf16 v[94:97], v[152:155], v[202:205], v[94:97]
	v_mfma_f32_16x16x32_bf16 v[90:93], v[156:159], v[198:201], 0
	v_mfma_f32_16x16x32_bf16 v[90:93], v[160:163], v[202:205], v[90:93]
	v_mfma_f32_16x16x32_bf16 v[74:77], v[156:159], v[206:209], 0
	v_mfma_f32_16x16x32_bf16 v[74:77], v[160:163], v[210:213], v[74:77]
	s_waitcnt lgkmcnt(0)
	v_mfma_f32_16x16x32_bf16 v[78:81], v[148:151], v[206:209], 0
	v_mfma_f32_16x16x32_bf16 v[78:81], v[152:155], v[210:213], v[78:81]
	s_setprio 0
	s_setprio 1
	v_mfma_f32_16x16x32_bf16 v[118:121], v[164:167], v[182:185], 0
	v_mfma_f32_16x16x32_bf16 v[118:121], v[168:171], v[186:189], v[118:121]
	v_mfma_f32_16x16x32_bf16 v[114:117], v[172:175], v[182:185], 0
	v_mfma_f32_16x16x32_bf16 v[114:117], v[176:179], v[186:189], v[114:117]
	v_mfma_f32_16x16x32_bf16 v[98:101], v[172:175], v[190:193], 0
	v_mfma_f32_16x16x32_bf16 v[98:101], v[176:179], v[194:197], v[98:101]
	v_mfma_f32_16x16x32_bf16 v[102:105], v[164:167], v[190:193], 0
	v_mfma_f32_16x16x32_bf16 v[102:105], v[168:171], v[194:197], v[102:105]
	v_mfma_f32_16x16x32_bf16 v[86:89], v[164:167], v[198:201], 0
	v_mfma_f32_16x16x32_bf16 v[86:89], v[168:171], v[202:205], v[86:89]
	v_mfma_f32_16x16x32_bf16 v[82:85], v[172:175], v[198:201], 0
	v_mfma_f32_16x16x32_bf16 v[82:85], v[176:179], v[202:205], v[82:85]
	v_mfma_f32_16x16x32_bf16 v[66:69], v[172:175], v[206:209], 0
	v_mfma_f32_16x16x32_bf16 v[66:69], v[176:179], v[210:213], v[66:69]
	s_setprio 2
	s_barrier
	v_mfma_f32_16x16x32_bf16 v[70:73], v[164:167], v[206:209], 0
	v_mfma_f32_16x16x32_bf16 v[70:73], v[168:171], v[210:213], v[70:73]
	s_setprio 0
	ds_read_b128 v[182:185], v145 offset:16384
	ds_read_b128 v[186:189], v145 offset:17408
	ds_read_b128 v[190:193], v145 offset:18432
	ds_read_b128 v[194:197], v145 offset:19456
	ds_read_b128 v[198:201], v145 offset:20480
	ds_read_b128 v[202:205], v145 offset:21504
	ds_read_b128 v[206:209], v145 offset:22528
	ds_read_b128 v[210:213], v145 offset:23552
	s_mov_b32 s74, m0
	s_mov_b32 m0, s35
	s_nop 0
	global_load_lds_dwordx4 v139, s[20:21]
	s_mov_b32 m0, s74
	s_nop 0
	s_mov_b32 s74, m0
	s_mov_b32 m0, s36
	s_nop 0
	global_load_lds_dwordx4 v141, s[20:21]
	s_mov_b32 m0, s74
	s_add_u32 s74, s20, 0x80000
	s_addc_u32 s75, s21, 0
	s_mov_b32 s76, m0
	s_mov_b32 m0, s37
	s_nop 0
	global_load_lds_dwordx4 v139, s[74:75]
	s_mov_b32 m0, s76
	s_nop 0
	s_mov_b32 s76, m0
	s_mov_b32 m0, s40
	s_nop 0
	global_load_lds_dwordx4 v141, s[74:75]
	s_mov_b32 m0, s76
	s_waitcnt vmcnt(4)
	s_waitcnt lgkmcnt(0)
	s_barrier
	s_setprio 1
	s_waitcnt lgkmcnt(7)
	v_mfma_f32_16x16x32_bf16 v[62:65], v[148:151], v[182:185], 0
	v_mfma_f32_16x16x32_bf16 v[62:65], v[152:155], v[186:189], v[62:65]
	s_waitcnt lgkmcnt(5)
	v_mfma_f32_16x16x32_bf16 v[58:61], v[156:159], v[182:185], 0
	v_mfma_f32_16x16x32_bf16 v[58:61], v[160:163], v[186:189], v[58:61]
	s_waitcnt lgkmcnt(3)
	v_mfma_f32_16x16x32_bf16 v[42:45], v[156:159], v[190:193], 0
	v_mfma_f32_16x16x32_bf16 v[42:45], v[160:163], v[194:197], v[42:45]
	s_waitcnt lgkmcnt(1)
	v_mfma_f32_16x16x32_bf16 v[46:49], v[148:151], v[190:193], 0
	v_mfma_f32_16x16x32_bf16 v[46:49], v[152:155], v[194:197], v[46:49]
	v_mfma_f32_16x16x32_bf16 v[30:33], v[148:151], v[198:201], 0
	v_mfma_f32_16x16x32_bf16 v[30:33], v[152:155], v[202:205], v[30:33]
	v_mfma_f32_16x16x32_bf16 v[26:29], v[156:159], v[198:201], 0
	v_mfma_f32_16x16x32_bf16 v[26:29], v[160:163], v[202:205], v[26:29]
	v_mfma_f32_16x16x32_bf16 v[10:13], v[156:159], v[206:209], 0
	v_mfma_f32_16x16x32_bf16 v[10:13], v[160:163], v[210:213], v[10:13]
	s_waitcnt lgkmcnt(0)
	v_mfma_f32_16x16x32_bf16 v[14:17], v[148:151], v[206:209], 0
	v_mfma_f32_16x16x32_bf16 v[14:17], v[152:155], v[210:213], v[14:17]
	s_setprio 0
	s_setprio 1
	v_mfma_f32_16x16x32_bf16 v[54:57], v[164:167], v[182:185], 0
	v_mfma_f32_16x16x32_bf16 v[54:57], v[168:171], v[186:189], v[54:57]
	v_mfma_f32_16x16x32_bf16 v[50:53], v[172:175], v[182:185], 0
	v_mfma_f32_16x16x32_bf16 v[50:53], v[176:179], v[186:189], v[50:53]
	v_mfma_f32_16x16x32_bf16 v[34:37], v[172:175], v[190:193], 0
	v_mfma_f32_16x16x32_bf16 v[34:37], v[176:179], v[194:197], v[34:37]
	v_mfma_f32_16x16x32_bf16 v[38:41], v[164:167], v[190:193], 0
	v_mfma_f32_16x16x32_bf16 v[38:41], v[168:171], v[194:197], v[38:41]
	v_mfma_f32_16x16x32_bf16 v[22:25], v[164:167], v[198:201], 0
	v_mfma_f32_16x16x32_bf16 v[22:25], v[168:171], v[202:205], v[22:25]
	v_mfma_f32_16x16x32_bf16 v[18:21], v[172:175], v[198:201], 0
	v_mfma_f32_16x16x32_bf16 v[18:21], v[176:179], v[202:205], v[18:21]
	v_mfma_f32_16x16x32_bf16 v[2:5], v[172:175], v[206:209], 0
	v_mfma_f32_16x16x32_bf16 v[2:5], v[176:179], v[210:213], v[2:5]
	s_setprio 2
	s_barrier
	v_mfma_f32_16x16x32_bf16 v[6:9], v[164:167], v[206:209], 0
	v_mfma_f32_16x16x32_bf16 v[6:9], v[168:171], v[210:213], v[6:9]
	s_setprio 0
	ds_read_b128 v[148:151], v146
	ds_read_b128 v[152:155], v146 offset:1024
	ds_read_b128 v[156:159], v146 offset:2048
	ds_read_b128 v[160:163], v146 offset:3072
	ds_read_b128 v[164:167], v147
	ds_read_b128 v[168:171], v147 offset:1024
	ds_read_b128 v[172:175], v147 offset:2048
	ds_read_b128 v[176:179], v147 offset:3072
	ds_read_b128 v[182:185], v145 offset:32768
	ds_read_b128 v[186:189], v145 offset:33792
	ds_read_b128 v[190:193], v145 offset:34816
	ds_read_b128 v[194:197], v145 offset:35840
	ds_read_b128 v[198:201], v145 offset:36864
	ds_read_b128 v[202:205], v145 offset:37888
	ds_read_b128 v[206:209], v145 offset:38912
	ds_read_b128 v[210:213], v145 offset:39936
	s_mov_b32 s74, m0
	s_mov_b32 m0, s31
	s_nop 0
	global_load_lds_dwordx4 v138, s[22:23]
	s_mov_b32 m0, s74
	s_nop 0
	s_mov_b32 s74, m0
	s_mov_b32 m0, s41
	s_nop 0
	global_load_lds_dwordx4 v140, s[22:23]
	s_mov_b32 m0, s74
	s_add_u32 s22, s22, 0x80000
	s_addc_u32 s23, s23, 0
	s_mov_b32 s74, m0
	s_mov_b32 m0, s42
	s_nop 0
	global_load_lds_dwordx4 v138, s[22:23]
	s_mov_b32 m0, s74
	s_nop 0
	s_mov_b32 s74, m0
	s_mov_b32 m0, s43
	s_nop 0
	global_load_lds_dwordx4 v140, s[22:23]
	s_mov_b32 m0, s74
	s_waitcnt vmcnt(8)
	s_waitcnt lgkmcnt(0)
	s_barrier
	s_setprio 1
	s_waitcnt lgkmcnt(7)
	v_mfma_f32_16x16x32_bf16 v[126:129], v[148:151], v[182:185], v[126:129]
	v_mfma_f32_16x16x32_bf16 v[126:129], v[152:155], v[186:189], v[126:129]
	s_waitcnt lgkmcnt(5)
	v_mfma_f32_16x16x32_bf16 v[122:125], v[156:159], v[182:185], v[122:125]
	v_mfma_f32_16x16x32_bf16 v[122:125], v[160:163], v[186:189], v[122:125]
	s_waitcnt lgkmcnt(3)
	v_mfma_f32_16x16x32_bf16 v[106:109], v[156:159], v[190:193], v[106:109]
	v_mfma_f32_16x16x32_bf16 v[106:109], v[160:163], v[194:197], v[106:109]
	s_waitcnt lgkmcnt(1)
	v_mfma_f32_16x16x32_bf16 v[110:113], v[148:151], v[190:193], v[110:113]
	v_mfma_f32_16x16x32_bf16 v[110:113], v[152:155], v[194:197], v[110:113]
	v_mfma_f32_16x16x32_bf16 v[94:97], v[148:151], v[198:201], v[94:97]
	v_mfma_f32_16x16x32_bf16 v[94:97], v[152:155], v[202:205], v[94:97]
	v_mfma_f32_16x16x32_bf16 v[90:93], v[156:159], v[198:201], v[90:93]
	v_mfma_f32_16x16x32_bf16 v[90:93], v[160:163], v[202:205], v[90:93]
	v_mfma_f32_16x16x32_bf16 v[74:77], v[156:159], v[206:209], v[74:77]
	v_mfma_f32_16x16x32_bf16 v[74:77], v[160:163], v[210:213], v[74:77]
	s_waitcnt lgkmcnt(0)
	v_mfma_f32_16x16x32_bf16 v[78:81], v[148:151], v[206:209], v[78:81]
	v_mfma_f32_16x16x32_bf16 v[78:81], v[152:155], v[210:213], v[78:81]
	s_setprio 0
	s_setprio 1
	v_mfma_f32_16x16x32_bf16 v[118:121], v[164:167], v[182:185], v[118:121]
	v_mfma_f32_16x16x32_bf16 v[118:121], v[168:171], v[186:189], v[118:121]
	v_mfma_f32_16x16x32_bf16 v[114:117], v[172:175], v[182:185], v[114:117]
	v_mfma_f32_16x16x32_bf16 v[114:117], v[176:179], v[186:189], v[114:117]
	v_mfma_f32_16x16x32_bf16 v[98:101], v[172:175], v[190:193], v[98:101]
	v_mfma_f32_16x16x32_bf16 v[98:101], v[176:179], v[194:197], v[98:101]
	v_mfma_f32_16x16x32_bf16 v[102:105], v[164:167], v[190:193], v[102:105]
	v_mfma_f32_16x16x32_bf16 v[102:105], v[168:171], v[194:197], v[102:105]
	v_mfma_f32_16x16x32_bf16 v[86:89], v[164:167], v[198:201], v[86:89]
	v_mfma_f32_16x16x32_bf16 v[86:89], v[168:171], v[202:205], v[86:89]
	v_mfma_f32_16x16x32_bf16 v[82:85], v[172:175], v[198:201], v[82:85]
	v_mfma_f32_16x16x32_bf16 v[82:85], v[176:179], v[202:205], v[82:85]
	v_mfma_f32_16x16x32_bf16 v[66:69], v[172:175], v[206:209], v[66:69]
	v_mfma_f32_16x16x32_bf16 v[66:69], v[176:179], v[210:213], v[66:69]
	s_setprio 2
	s_barrier
	v_mfma_f32_16x16x32_bf16 v[70:73], v[164:167], v[206:209], v[70:73]
	v_mfma_f32_16x16x32_bf16 v[70:73], v[168:171], v[210:213], v[70:73]
	s_setprio 0
	ds_read_b128 v[182:185], v145 offset:49152
	ds_read_b128 v[186:189], v145 offset:50176
	ds_read_b128 v[190:193], v145 offset:51200
	ds_read_b128 v[194:197], v145 offset:52224
	ds_read_b128 v[198:201], v145 offset:53248
	ds_read_b128 v[202:205], v145 offset:54272
	ds_read_b128 v[206:209], v145 offset:55296
	ds_read_b128 v[210:213], v145 offset:56320
	s_add_u32 s22, s20, 0x80
	s_addc_u32 s23, s21, 0
	s_mov_b32 s74, m0
	s_mov_b32 m0, s46
	s_nop 0
	global_load_lds_dwordx4 v139, s[22:23]
	s_mov_b32 m0, s74
	s_add_u32 s20, s20, 0x80080
	s_mov_b32 s74, m0
	s_mov_b32 m0, s47
	s_nop 0
	global_load_lds_dwordx4 v141, s[22:23]
	s_mov_b32 m0, s74
	s_addc_u32 s21, s21, 0
	s_mov_b32 s22, m0
	s_mov_b32 m0, s48
	s_nop 0
	global_load_lds_dwordx4 v139, s[20:21]
	s_mov_b32 m0, s22
	s_nop 0
	s_mov_b32 s22, m0
	s_mov_b32 m0, s49
	s_nop 0
	global_load_lds_dwordx4 v141, s[20:21]
	s_mov_b32 m0, s22
	s_waitcnt vmcnt(4)
	s_waitcnt lgkmcnt(0)
	s_barrier
	s_setprio 1
	s_waitcnt lgkmcnt(7)
	v_mfma_f32_16x16x32_bf16 v[62:65], v[148:151], v[182:185], v[62:65]
	v_mfma_f32_16x16x32_bf16 v[62:65], v[152:155], v[186:189], v[62:65]
	s_waitcnt lgkmcnt(5)
	v_mfma_f32_16x16x32_bf16 v[58:61], v[156:159], v[182:185], v[58:61]
	v_mfma_f32_16x16x32_bf16 v[58:61], v[160:163], v[186:189], v[58:61]
	s_waitcnt lgkmcnt(3)
	v_mfma_f32_16x16x32_bf16 v[42:45], v[156:159], v[190:193], v[42:45]
	v_mfma_f32_16x16x32_bf16 v[42:45], v[160:163], v[194:197], v[42:45]
	s_waitcnt lgkmcnt(1)
	v_mfma_f32_16x16x32_bf16 v[46:49], v[148:151], v[190:193], v[46:49]
	v_mfma_f32_16x16x32_bf16 v[46:49], v[152:155], v[194:197], v[46:49]
	v_mfma_f32_16x16x32_bf16 v[30:33], v[148:151], v[198:201], v[30:33]
	v_mfma_f32_16x16x32_bf16 v[30:33], v[152:155], v[202:205], v[30:33]
	v_mfma_f32_16x16x32_bf16 v[26:29], v[156:159], v[198:201], v[26:29]
	v_mfma_f32_16x16x32_bf16 v[26:29], v[160:163], v[202:205], v[26:29]
	v_mfma_f32_16x16x32_bf16 v[10:13], v[156:159], v[206:209], v[10:13]
	v_mfma_f32_16x16x32_bf16 v[10:13], v[160:163], v[210:213], v[10:13]
	s_waitcnt lgkmcnt(0)
	v_mfma_f32_16x16x32_bf16 v[14:17], v[148:151], v[206:209], v[14:17]
	v_mfma_f32_16x16x32_bf16 v[14:17], v[152:155], v[210:213], v[14:17]
	s_setprio 0
	s_setprio 1
	v_mfma_f32_16x16x32_bf16 v[54:57], v[164:167], v[182:185], v[54:57]
	v_mfma_f32_16x16x32_bf16 v[54:57], v[168:171], v[186:189], v[54:57]
	v_mfma_f32_16x16x32_bf16 v[50:53], v[172:175], v[182:185], v[50:53]
	v_mfma_f32_16x16x32_bf16 v[50:53], v[176:179], v[186:189], v[50:53]
	v_mfma_f32_16x16x32_bf16 v[34:37], v[172:175], v[190:193], v[34:37]
	v_mfma_f32_16x16x32_bf16 v[34:37], v[176:179], v[194:197], v[34:37]
	v_mfma_f32_16x16x32_bf16 v[38:41], v[164:167], v[190:193], v[38:41]
	v_mfma_f32_16x16x32_bf16 v[38:41], v[168:171], v[194:197], v[38:41]
	v_mfma_f32_16x16x32_bf16 v[22:25], v[164:167], v[198:201], v[22:25]
	v_mfma_f32_16x16x32_bf16 v[22:25], v[168:171], v[202:205], v[22:25]
	v_mfma_f32_16x16x32_bf16 v[18:21], v[172:175], v[198:201], v[18:21]
	v_mfma_f32_16x16x32_bf16 v[18:21], v[176:179], v[202:205], v[18:21]
	v_mfma_f32_16x16x32_bf16 v[2:5], v[172:175], v[206:209], v[2:5]
	v_mfma_f32_16x16x32_bf16 v[2:5], v[176:179], v[210:213], v[2:5]
	s_setprio 2
	s_barrier
	v_mfma_f32_16x16x32_bf16 v[6:9], v[164:167], v[206:209], v[6:9]
	v_mfma_f32_16x16x32_bf16 v[6:9], v[168:171], v[210:213], v[6:9]
	s_setprio 0
	s_add_i32 s73, s73, 2
	s_add_u32 s66, s66, 0x100
	s_addc_u32 s67, s67, 0
	s_add_u32 s18, s18, 0x100
	s_addc_u32 s19, s19, 0
	s_add_u32 s70, s70, 0x100
	s_addc_u32 s71, s71, 0
	s_cmp_gt_u32 s73, 29
	.p2align 6
.LBB0_1785:
	ds_read_b128 v[148:151], v143
	ds_read_b128 v[152:155], v143 offset:1024
	ds_read_b128 v[156:159], v143 offset:2048
	ds_read_b128 v[160:163], v143 offset:3072
	ds_read_b128 v[164:167], v144
	ds_read_b128 v[168:171], v144 offset:1024
	ds_read_b128 v[172:175], v144 offset:2048
	ds_read_b128 v[176:179], v144 offset:3072
	s_cmp_eq_u32 s73, 28
	s_cselect_b32 s21, s9, s67
	s_cselect_b32 s20, s65, s66
	s_cselect_b32 s23, s11, s71
	s_cselect_b32 s22, s64, s70
	ds_read_b128 v[182:185], v145
	ds_read_b128 v[186:189], v145 offset:1024
	ds_read_b128 v[190:193], v145 offset:2048
	ds_read_b128 v[194:197], v145 offset:3072
	ds_read_b128 v[198:201], v145 offset:4096
	ds_read_b128 v[202:205], v145 offset:5120
	ds_read_b128 v[206:209], v145 offset:6144
	ds_read_b128 v[210:213], v145 offset:7168
	s_add_u32 s74, s18, 0xfff80000
	s_addc_u32 s75, s19, -1
	s_mov_b32 s76, m0
	s_mov_b32 m0, s56
	s_nop 0
	global_load_lds_dwordx4 v138, s[74:75]
	s_mov_b32 m0, s76
	s_nop 0
	s_mov_b32 s76, m0
	s_mov_b32 m0, s59
	s_nop 0
	global_load_lds_dwordx4 v140, s[74:75]
	s_mov_b32 m0, s76
	s_mov_b32 s74, m0
	s_mov_b32 m0, s57
	s_nop 0
	global_load_lds_dwordx4 v138, s[18:19]
	s_mov_b32 m0, s74
	s_nop 0
	s_mov_b32 s74, m0
	s_mov_b32 m0, s62
	s_nop 0
	global_load_lds_dwordx4 v140, s[18:19]
	s_mov_b32 m0, s74
	s_waitcnt vmcnt(8)
	s_waitcnt lgkmcnt(0)
	s_barrier
	s_setprio 1
	s_waitcnt lgkmcnt(7)
	v_mfma_f32_16x16x32_bf16 v[126:129], v[148:151], v[182:185], v[126:129]
	v_mfma_f32_16x16x32_bf16 v[126:129], v[152:155], v[186:189], v[126:129]
	s_waitcnt lgkmcnt(5)
	v_mfma_f32_16x16x32_bf16 v[122:125], v[156:159], v[182:185], v[122:125]
	v_mfma_f32_16x16x32_bf16 v[122:125], v[160:163], v[186:189], v[122:125]
	s_waitcnt lgkmcnt(3)
	v_mfma_f32_16x16x32_bf16 v[106:109], v[156:159], v[190:193], v[106:109]
	v_mfma_f32_16x16x32_bf16 v[106:109], v[160:163], v[194:197], v[106:109]
	s_waitcnt lgkmcnt(1)
	v_mfma_f32_16x16x32_bf16 v[110:113], v[148:151], v[190:193], v[110:113]
	v_mfma_f32_16x16x32_bf16 v[110:113], v[152:155], v[194:197], v[110:113]
	v_mfma_f32_16x16x32_bf16 v[94:97], v[148:151], v[198:201], v[94:97]
	v_mfma_f32_16x16x32_bf16 v[94:97], v[152:155], v[202:205], v[94:97]
	v_mfma_f32_16x16x32_bf16 v[90:93], v[156:159], v[198:201], v[90:93]
	v_mfma_f32_16x16x32_bf16 v[90:93], v[160:163], v[202:205], v[90:93]
	v_mfma_f32_16x16x32_bf16 v[74:77], v[156:159], v[206:209], v[74:77]
	v_mfma_f32_16x16x32_bf16 v[74:77], v[160:163], v[210:213], v[74:77]
	s_waitcnt lgkmcnt(0)
	v_mfma_f32_16x16x32_bf16 v[78:81], v[148:151], v[206:209], v[78:81]
	v_mfma_f32_16x16x32_bf16 v[78:81], v[152:155], v[210:213], v[78:81]
	s_setprio 0
	s_setprio 1
	v_mfma_f32_16x16x32_bf16 v[118:121], v[164:167], v[182:185], v[118:121]
	v_mfma_f32_16x16x32_bf16 v[118:121], v[168:171], v[186:189], v[118:121]
	v_mfma_f32_16x16x32_bf16 v[114:117], v[172:175], v[182:185], v[114:117]
	v_mfma_f32_16x16x32_bf16 v[114:117], v[176:179], v[186:189], v[114:117]
	v_mfma_f32_16x16x32_bf16 v[98:101], v[172:175], v[190:193], v[98:101]
	v_mfma_f32_16x16x32_bf16 v[98:101], v[176:179], v[194:197], v[98:101]
	v_mfma_f32_16x16x32_bf16 v[102:105], v[164:167], v[190:193], v[102:105]
	v_mfma_f32_16x16x32_bf16 v[102:105], v[168:171], v[194:197], v[102:105]
	v_mfma_f32_16x16x32_bf16 v[86:89], v[164:167], v[198:201], v[86:89]
	v_mfma_f32_16x16x32_bf16 v[86:89], v[168:171], v[202:205], v[86:89]
	v_mfma_f32_16x16x32_bf16 v[82:85], v[172:175], v[198:201], v[82:85]
	v_mfma_f32_16x16x32_bf16 v[82:85], v[176:179], v[202:205], v[82:85]
	v_mfma_f32_16x16x32_bf16 v[66:69], v[172:175], v[206:209], v[66:69]
	v_mfma_f32_16x16x32_bf16 v[66:69], v[176:179], v[210:213], v[66:69]
	s_setprio 2
	s_barrier
	v_mfma_f32_16x16x32_bf16 v[70:73], v[164:167], v[206:209], v[70:73]
	v_mfma_f32_16x16x32_bf16 v[70:73], v[168:171], v[210:213], v[70:73]
	s_setprio 0
	ds_read_b128 v[182:185], v145 offset:16384
	ds_read_b128 v[186:189], v145 offset:17408
	ds_read_b128 v[190:193], v145 offset:18432
	ds_read_b128 v[194:197], v145 offset:19456
	ds_read_b128 v[198:201], v145 offset:20480
	ds_read_b128 v[202:205], v145 offset:21504
	ds_read_b128 v[206:209], v145 offset:22528
	ds_read_b128 v[210:213], v145 offset:23552
	s_mov_b32 s74, m0
	s_mov_b32 m0, s35
	s_nop 0
	global_load_lds_dwordx4 v139, s[20:21]
	s_mov_b32 m0, s74
	s_nop 0
	s_mov_b32 s74, m0
	s_mov_b32 m0, s36
	s_nop 0
	global_load_lds_dwordx4 v141, s[20:21]
	s_mov_b32 m0, s74
	s_add_u32 s74, s20, 0x80000
	s_addc_u32 s75, s21, 0
	s_mov_b32 s76, m0
	s_mov_b32 m0, s37
	s_nop 0
	global_load_lds_dwordx4 v139, s[74:75]
	s_mov_b32 m0, s76
	s_nop 0
	s_mov_b32 s76, m0
	s_mov_b32 m0, s40
	s_nop 0
	global_load_lds_dwordx4 v141, s[74:75]
	s_mov_b32 m0, s76
	s_waitcnt vmcnt(4)
	s_waitcnt lgkmcnt(0)
	s_barrier
	s_setprio 1
	s_waitcnt lgkmcnt(7)
	v_mfma_f32_16x16x32_bf16 v[62:65], v[148:151], v[182:185], v[62:65]
	v_mfma_f32_16x16x32_bf16 v[62:65], v[152:155], v[186:189], v[62:65]
	s_waitcnt lgkmcnt(5)
	v_mfma_f32_16x16x32_bf16 v[58:61], v[156:159], v[182:185], v[58:61]
	v_mfma_f32_16x16x32_bf16 v[58:61], v[160:163], v[186:189], v[58:61]
	s_waitcnt lgkmcnt(3)
	v_mfma_f32_16x16x32_bf16 v[42:45], v[156:159], v[190:193], v[42:45]
	v_mfma_f32_16x16x32_bf16 v[42:45], v[160:163], v[194:197], v[42:45]
	s_waitcnt lgkmcnt(1)
	v_mfma_f32_16x16x32_bf16 v[46:49], v[148:151], v[190:193], v[46:49]
	v_mfma_f32_16x16x32_bf16 v[46:49], v[152:155], v[194:197], v[46:49]
	v_mfma_f32_16x16x32_bf16 v[30:33], v[148:151], v[198:201], v[30:33]
	v_mfma_f32_16x16x32_bf16 v[30:33], v[152:155], v[202:205], v[30:33]
	v_mfma_f32_16x16x32_bf16 v[26:29], v[156:159], v[198:201], v[26:29]
	v_mfma_f32_16x16x32_bf16 v[26:29], v[160:163], v[202:205], v[26:29]
	v_mfma_f32_16x16x32_bf16 v[10:13], v[156:159], v[206:209], v[10:13]
	v_mfma_f32_16x16x32_bf16 v[10:13], v[160:163], v[210:213], v[10:13]
	s_waitcnt lgkmcnt(0)
	v_mfma_f32_16x16x32_bf16 v[14:17], v[148:151], v[206:209], v[14:17]
	v_mfma_f32_16x16x32_bf16 v[14:17], v[152:155], v[210:213], v[14:17]
	s_setprio 0
	s_setprio 1
	v_mfma_f32_16x16x32_bf16 v[54:57], v[164:167], v[182:185], v[54:57]
	v_mfma_f32_16x16x32_bf16 v[54:57], v[168:171], v[186:189], v[54:57]
	v_mfma_f32_16x16x32_bf16 v[50:53], v[172:175], v[182:185], v[50:53]
	v_mfma_f32_16x16x32_bf16 v[50:53], v[176:179], v[186:189], v[50:53]
	v_mfma_f32_16x16x32_bf16 v[34:37], v[172:175], v[190:193], v[34:37]
	v_mfma_f32_16x16x32_bf16 v[34:37], v[176:179], v[194:197], v[34:37]
	v_mfma_f32_16x16x32_bf16 v[38:41], v[164:167], v[190:193], v[38:41]
	v_mfma_f32_16x16x32_bf16 v[38:41], v[168:171], v[194:197], v[38:41]
	v_mfma_f32_16x16x32_bf16 v[22:25], v[164:167], v[198:201], v[22:25]
	v_mfma_f32_16x16x32_bf16 v[22:25], v[168:171], v[202:205], v[22:25]
	v_mfma_f32_16x16x32_bf16 v[18:21], v[172:175], v[198:201], v[18:21]
	v_mfma_f32_16x16x32_bf16 v[18:21], v[176:179], v[202:205], v[18:21]
	v_mfma_f32_16x16x32_bf16 v[2:5], v[172:175], v[206:209], v[2:5]
	v_mfma_f32_16x16x32_bf16 v[2:5], v[176:179], v[210:213], v[2:5]
	s_setprio 2
	s_barrier
	v_mfma_f32_16x16x32_bf16 v[6:9], v[164:167], v[206:209], v[6:9]
	v_mfma_f32_16x16x32_bf16 v[6:9], v[168:171], v[210:213], v[6:9]
	s_setprio 0
	ds_read_b128 v[148:151], v146
	ds_read_b128 v[152:155], v146 offset:1024
	ds_read_b128 v[156:159], v146 offset:2048
	ds_read_b128 v[160:163], v146 offset:3072
	ds_read_b128 v[164:167], v147
	ds_read_b128 v[168:171], v147 offset:1024
	ds_read_b128 v[172:175], v147 offset:2048
	ds_read_b128 v[176:179], v147 offset:3072
	ds_read_b128 v[182:185], v145 offset:32768
	ds_read_b128 v[186:189], v145 offset:33792
	ds_read_b128 v[190:193], v145 offset:34816
	ds_read_b128 v[194:197], v145 offset:35840
	ds_read_b128 v[198:201], v145 offset:36864
	ds_read_b128 v[202:205], v145 offset:37888
	ds_read_b128 v[206:209], v145 offset:38912
	ds_read_b128 v[210:213], v145 offset:39936
	s_mov_b32 s74, m0
	s_mov_b32 m0, s31
	s_nop 0
	global_load_lds_dwordx4 v138, s[22:23]
	s_mov_b32 m0, s74
	s_nop 0
	s_mov_b32 s74, m0
	s_mov_b32 m0, s41
	s_nop 0
	global_load_lds_dwordx4 v140, s[22:23]
	s_mov_b32 m0, s74
	s_add_u32 s22, s22, 0x80000
	s_addc_u32 s23, s23, 0
	s_mov_b32 s74, m0
	s_mov_b32 m0, s42
	s_nop 0
	global_load_lds_dwordx4 v138, s[22:23]
	s_mov_b32 m0, s74
	s_nop 0
	s_mov_b32 s74, m0
	s_mov_b32 m0, s43
	s_nop 0
	global_load_lds_dwordx4 v140, s[22:23]
	s_mov_b32 m0, s74
	s_waitcnt vmcnt(8)
	s_waitcnt lgkmcnt(0)
	s_barrier
	s_setprio 1
	s_waitcnt lgkmcnt(7)
	v_mfma_f32_16x16x32_bf16 v[126:129], v[148:151], v[182:185], v[126:129]
	v_mfma_f32_16x16x32_bf16 v[126:129], v[152:155], v[186:189], v[126:129]
	s_waitcnt lgkmcnt(5)
	v_mfma_f32_16x16x32_bf16 v[122:125], v[156:159], v[182:185], v[122:125]
	v_mfma_f32_16x16x32_bf16 v[122:125], v[160:163], v[186:189], v[122:125]
	s_waitcnt lgkmcnt(3)
	v_mfma_f32_16x16x32_bf16 v[106:109], v[156:159], v[190:193], v[106:109]
	v_mfma_f32_16x16x32_bf16 v[106:109], v[160:163], v[194:197], v[106:109]
	s_waitcnt lgkmcnt(1)
	v_mfma_f32_16x16x32_bf16 v[110:113], v[148:151], v[190:193], v[110:113]
	v_mfma_f32_16x16x32_bf16 v[110:113], v[152:155], v[194:197], v[110:113]
	v_mfma_f32_16x16x32_bf16 v[94:97], v[148:151], v[198:201], v[94:97]
	v_mfma_f32_16x16x32_bf16 v[94:97], v[152:155], v[202:205], v[94:97]
	v_mfma_f32_16x16x32_bf16 v[90:93], v[156:159], v[198:201], v[90:93]
	v_mfma_f32_16x16x32_bf16 v[90:93], v[160:163], v[202:205], v[90:93]
	v_mfma_f32_16x16x32_bf16 v[74:77], v[156:159], v[206:209], v[74:77]
	v_mfma_f32_16x16x32_bf16 v[74:77], v[160:163], v[210:213], v[74:77]
	s_waitcnt lgkmcnt(0)
	v_mfma_f32_16x16x32_bf16 v[78:81], v[148:151], v[206:209], v[78:81]
	v_mfma_f32_16x16x32_bf16 v[78:81], v[152:155], v[210:213], v[78:81]
	s_setprio 0
	s_setprio 1
	v_mfma_f32_16x16x32_bf16 v[118:121], v[164:167], v[182:185], v[118:121]
	v_mfma_f32_16x16x32_bf16 v[118:121], v[168:171], v[186:189], v[118:121]
	v_mfma_f32_16x16x32_bf16 v[114:117], v[172:175], v[182:185], v[114:117]
	v_mfma_f32_16x16x32_bf16 v[114:117], v[176:179], v[186:189], v[114:117]
	v_mfma_f32_16x16x32_bf16 v[98:101], v[172:175], v[190:193], v[98:101]
	v_mfma_f32_16x16x32_bf16 v[98:101], v[176:179], v[194:197], v[98:101]
	v_mfma_f32_16x16x32_bf16 v[102:105], v[164:167], v[190:193], v[102:105]
	v_mfma_f32_16x16x32_bf16 v[102:105], v[168:171], v[194:197], v[102:105]
	v_mfma_f32_16x16x32_bf16 v[86:89], v[164:167], v[198:201], v[86:89]
	v_mfma_f32_16x16x32_bf16 v[86:89], v[168:171], v[202:205], v[86:89]
	v_mfma_f32_16x16x32_bf16 v[82:85], v[172:175], v[198:201], v[82:85]
	v_mfma_f32_16x16x32_bf16 v[82:85], v[176:179], v[202:205], v[82:85]
	v_mfma_f32_16x16x32_bf16 v[66:69], v[172:175], v[206:209], v[66:69]
	v_mfma_f32_16x16x32_bf16 v[66:69], v[176:179], v[210:213], v[66:69]
	s_setprio 2
	s_barrier
	v_mfma_f32_16x16x32_bf16 v[70:73], v[164:167], v[206:209], v[70:73]
	v_mfma_f32_16x16x32_bf16 v[70:73], v[168:171], v[210:213], v[70:73]
	s_setprio 0
	ds_read_b128 v[182:185], v145 offset:49152
	ds_read_b128 v[186:189], v145 offset:50176
	ds_read_b128 v[190:193], v145 offset:51200
	ds_read_b128 v[194:197], v145 offset:52224
	ds_read_b128 v[198:201], v145 offset:53248
	ds_read_b128 v[202:205], v145 offset:54272
	ds_read_b128 v[206:209], v145 offset:55296
	ds_read_b128 v[210:213], v145 offset:56320
	s_add_u32 s22, s20, 0x80
	s_addc_u32 s23, s21, 0
	s_mov_b32 s74, m0
	s_mov_b32 m0, s46
	s_nop 0
	global_load_lds_dwordx4 v139, s[22:23]
	s_mov_b32 m0, s74
	s_add_u32 s20, s20, 0x80080
	s_mov_b32 s74, m0
	s_mov_b32 m0, s47
	s_nop 0
	global_load_lds_dwordx4 v141, s[22:23]
	s_mov_b32 m0, s74
	s_addc_u32 s21, s21, 0
	s_mov_b32 s22, m0
	s_mov_b32 m0, s48
	s_nop 0
	global_load_lds_dwordx4 v139, s[20:21]
	s_mov_b32 m0, s22
	s_nop 0
	s_mov_b32 s22, m0
	s_mov_b32 m0, s49
	s_nop 0
	global_load_lds_dwordx4 v141, s[20:21]
	s_mov_b32 m0, s22
	s_waitcnt vmcnt(4)
	s_waitcnt lgkmcnt(0)
	s_barrier
	s_setprio 1
	s_waitcnt lgkmcnt(7)
	v_mfma_f32_16x16x32_bf16 v[62:65], v[148:151], v[182:185], v[62:65]
	v_mfma_f32_16x16x32_bf16 v[62:65], v[152:155], v[186:189], v[62:65]
	s_waitcnt lgkmcnt(5)
	v_mfma_f32_16x16x32_bf16 v[58:61], v[156:159], v[182:185], v[58:61]
	v_mfma_f32_16x16x32_bf16 v[58:61], v[160:163], v[186:189], v[58:61]
	s_waitcnt lgkmcnt(3)
	v_mfma_f32_16x16x32_bf16 v[42:45], v[156:159], v[190:193], v[42:45]
	v_mfma_f32_16x16x32_bf16 v[42:45], v[160:163], v[194:197], v[42:45]
	s_waitcnt lgkmcnt(1)
	v_mfma_f32_16x16x32_bf16 v[46:49], v[148:151], v[190:193], v[46:49]
	v_mfma_f32_16x16x32_bf16 v[46:49], v[152:155], v[194:197], v[46:49]
	v_mfma_f32_16x16x32_bf16 v[30:33], v[148:151], v[198:201], v[30:33]
	v_mfma_f32_16x16x32_bf16 v[30:33], v[152:155], v[202:205], v[30:33]
	v_mfma_f32_16x16x32_bf16 v[26:29], v[156:159], v[198:201], v[26:29]
	v_mfma_f32_16x16x32_bf16 v[26:29], v[160:163], v[202:205], v[26:29]
	v_mfma_f32_16x16x32_bf16 v[10:13], v[156:159], v[206:209], v[10:13]
	v_mfma_f32_16x16x32_bf16 v[10:13], v[160:163], v[210:213], v[10:13]
	s_waitcnt lgkmcnt(0)
	v_mfma_f32_16x16x32_bf16 v[14:17], v[148:151], v[206:209], v[14:17]
	v_mfma_f32_16x16x32_bf16 v[14:17], v[152:155], v[210:213], v[14:17]
	s_setprio 0
	s_setprio 1
	v_mfma_f32_16x16x32_bf16 v[54:57], v[164:167], v[182:185], v[54:57]
	v_mfma_f32_16x16x32_bf16 v[54:57], v[168:171], v[186:189], v[54:57]
	v_mfma_f32_16x16x32_bf16 v[50:53], v[172:175], v[182:185], v[50:53]
	v_mfma_f32_16x16x32_bf16 v[50:53], v[176:179], v[186:189], v[50:53]
	v_mfma_f32_16x16x32_bf16 v[34:37], v[172:175], v[190:193], v[34:37]
	v_mfma_f32_16x16x32_bf16 v[34:37], v[176:179], v[194:197], v[34:37]
	v_mfma_f32_16x16x32_bf16 v[38:41], v[164:167], v[190:193], v[38:41]
	v_mfma_f32_16x16x32_bf16 v[38:41], v[168:171], v[194:197], v[38:41]
	v_mfma_f32_16x16x32_bf16 v[22:25], v[164:167], v[198:201], v[22:25]
	v_mfma_f32_16x16x32_bf16 v[22:25], v[168:171], v[202:205], v[22:25]
	v_mfma_f32_16x16x32_bf16 v[18:21], v[172:175], v[198:201], v[18:21]
	v_mfma_f32_16x16x32_bf16 v[18:21], v[176:179], v[202:205], v[18:21]
	v_mfma_f32_16x16x32_bf16 v[2:5], v[172:175], v[206:209], v[2:5]
	v_mfma_f32_16x16x32_bf16 v[2:5], v[176:179], v[210:213], v[2:5]
	s_setprio 2
	s_barrier
	v_mfma_f32_16x16x32_bf16 v[6:9], v[164:167], v[206:209], v[6:9]
	v_mfma_f32_16x16x32_bf16 v[6:9], v[168:171], v[210:213], v[6:9]
	s_setprio 0
	s_add_i32 s73, s73, 2
	s_add_u32 s66, s66, 0x100
	s_addc_u32 s67, s67, 0
	s_add_u32 s18, s18, 0x100
	s_addc_u32 s19, s19, 0
	s_add_u32 s70, s70, 0x100
	s_addc_u32 s71, s71, 0
	s_cmp_gt_u32 s73, 29
	s_cbranch_scc0 .LBB0_1785
	v_mov_b32_e32 v212, v252
	v_mov_b32_e32 v213, v253
	s_and_b64 vcc, exec, s[6:7]
	s_cbranch_vccz .LBB0_1788
	s_barrier

.LBB0_2593:
	s_ashr_i32 s11, s10, 31
	s_lshl_b64 s[12:13], s[10:11], 20
	s_add_u32 s12, s26, s12
	s_addc_u32 s13, s27, s13
	s_and_b64 s[14:15], s[2:3], exec
	s_cselect_b32 s11, s13, s21
	s_cselect_b32 s62, s12, s20
	s_ashr_i32 s9, s8, 31
	s_lshl_b64 s[14:15], s[8:9], 20
	s_add_u32 s14, s28, s14
	s_addc_u32 s15, s29, s15
	s_and_b64 s[22:23], s[2:3], exec
	s_cselect_b32 s9, s15, s19
	s_cselect_b32 s63, s14, s18
	s_add_u32 s64, s18, 0x100
	s_addc_u32 s65, s19, 0
	s_add_u32 s18, s20, 0x80080
	s_addc_u32 s19, s21, 0
	s_add_u32 s66, s20, 0x100
	s_addc_u32 s67, s21, 0
	s_mov_b32 s70, -2
	v_mov_b32_e32 v252, v212
	v_mov_b32_e32 v253, v213
	ds_read_b128 v[148:151], v143
	ds_read_b128 v[152:155], v143 offset:1024
	ds_read_b128 v[156:159], v143 offset:2048
	ds_read_b128 v[160:163], v143 offset:3072
	ds_read_b128 v[164:167], v144
	ds_read_b128 v[168:171], v144 offset:1024
	ds_read_b128 v[172:175], v144 offset:2048
	ds_read_b128 v[176:179], v144 offset:3072
	s_cmp_eq_u32 s70, 28
	s_cselect_b32 s21, s9, s65
	s_cselect_b32 s20, s63, s64
	s_cselect_b32 s23, s11, s67
	s_cselect_b32 s22, s62, s66
	ds_read_b128 v[182:185], v145
	ds_read_b128 v[186:189], v145 offset:1024
	ds_read_b128 v[190:193], v145 offset:2048
	ds_read_b128 v[194:197], v145 offset:3072
	ds_read_b128 v[198:201], v145 offset:4096
	ds_read_b128 v[202:205], v145 offset:5120
	ds_read_b128 v[206:209], v145 offset:6144
	ds_read_b128 v[210:213], v145 offset:7168
	s_add_u32 s74, s18, 0xfff80000
	s_addc_u32 s75, s19, -1
	s_mov_b32 s71, m0
	s_mov_b32 m0, s48
	s_nop 0
	global_load_lds_dwordx4 v138, s[74:75]
	s_mov_b32 m0, s71
	s_nop 0
	s_mov_b32 s71, m0
	s_mov_b32 m0, s57
	s_nop 0
	global_load_lds_dwordx4 v140, s[74:75]
	s_mov_b32 m0, s71
	s_nop 0
	s_mov_b32 s71, m0
	s_mov_b32 m0, s49
	s_nop 0
	global_load_lds_dwordx4 v138, s[18:19]
	s_mov_b32 m0, s71
	s_nop 0
	s_mov_b32 s71, m0
	s_mov_b32 m0, s58
	s_nop 0
	global_load_lds_dwordx4 v140, s[18:19]
	s_mov_b32 m0, s71
	s_waitcnt vmcnt(8)
	s_waitcnt lgkmcnt(0)
	s_barrier
	s_setprio 1
	s_waitcnt lgkmcnt(7)
	v_mfma_f32_16x16x32_bf16 v[126:129], v[148:151], v[182:185], 0
	v_mfma_f32_16x16x32_bf16 v[126:129], v[152:155], v[186:189], v[126:129]
	s_waitcnt lgkmcnt(5)
	v_mfma_f32_16x16x32_bf16 v[122:125], v[156:159], v[182:185], 0
	v_mfma_f32_16x16x32_bf16 v[122:125], v[160:163], v[186:189], v[122:125]
	s_waitcnt lgkmcnt(3)
	v_mfma_f32_16x16x32_bf16 v[106:109], v[156:159], v[190:193], 0
	v_mfma_f32_16x16x32_bf16 v[106:109], v[160:163], v[194:197], v[106:109]
	s_waitcnt lgkmcnt(1)
	v_mfma_f32_16x16x32_bf16 v[110:113], v[148:151], v[190:193], 0
	v_mfma_f32_16x16x32_bf16 v[110:113], v[152:155], v[194:197], v[110:113]
	v_mfma_f32_16x16x32_bf16 v[94:97], v[148:151], v[198:201], 0
	v_mfma_f32_16x16x32_bf16 v[94:97], v[152:155], v[202:205], v[94:97]
	v_mfma_f32_16x16x32_bf16 v[90:93], v[156:159], v[198:201], 0
	v_mfma_f32_16x16x32_bf16 v[90:93], v[160:163], v[202:205], v[90:93]
	v_mfma_f32_16x16x32_bf16 v[74:77], v[156:159], v[206:209], 0
	v_mfma_f32_16x16x32_bf16 v[74:77], v[160:163], v[210:213], v[74:77]
	s_waitcnt lgkmcnt(0)
	v_mfma_f32_16x16x32_bf16 v[78:81], v[148:151], v[206:209], 0
	v_mfma_f32_16x16x32_bf16 v[78:81], v[152:155], v[210:213], v[78:81]
	s_setprio 0
	s_setprio 1
	v_mfma_f32_16x16x32_bf16 v[118:121], v[164:167], v[182:185], 0
	v_mfma_f32_16x16x32_bf16 v[118:121], v[168:171], v[186:189], v[118:121]
	v_mfma_f32_16x16x32_bf16 v[114:117], v[172:175], v[182:185], 0
	v_mfma_f32_16x16x32_bf16 v[114:117], v[176:179], v[186:189], v[114:117]
	v_mfma_f32_16x16x32_bf16 v[98:101], v[172:175], v[190:193], 0
	v_mfma_f32_16x16x32_bf16 v[98:101], v[176:179], v[194:197], v[98:101]
	v_mfma_f32_16x16x32_bf16 v[102:105], v[164:167], v[190:193], 0
	v_mfma_f32_16x16x32_bf16 v[102:105], v[168:171], v[194:197], v[102:105]
	v_mfma_f32_16x16x32_bf16 v[86:89], v[164:167], v[198:201], 0
	v_mfma_f32_16x16x32_bf16 v[86:89], v[168:171], v[202:205], v[86:89]
	v_mfma_f32_16x16x32_bf16 v[82:85], v[172:175], v[198:201], 0
	v_mfma_f32_16x16x32_bf16 v[82:85], v[176:179], v[202:205], v[82:85]
	v_mfma_f32_16x16x32_bf16 v[66:69], v[172:175], v[206:209], 0
	v_mfma_f32_16x16x32_bf16 v[66:69], v[176:179], v[210:213], v[66:69]
	s_setprio 2
	s_barrier
	v_mfma_f32_16x16x32_bf16 v[70:73], v[164:167], v[206:209], 0
	v_mfma_f32_16x16x32_bf16 v[70:73], v[168:171], v[210:213], v[70:73]
	s_setprio 0
	ds_read_b128 v[182:185], v145 offset:16384
	ds_read_b128 v[186:189], v145 offset:17408
	ds_read_b128 v[190:193], v145 offset:18432
	ds_read_b128 v[194:197], v145 offset:19456
	ds_read_b128 v[198:201], v145 offset:20480
	ds_read_b128 v[202:205], v145 offset:21504
	ds_read_b128 v[206:209], v145 offset:22528
	ds_read_b128 v[210:213], v145 offset:23552
	s_mov_b32 s71, m0
	s_mov_b32 m0, s35
	s_nop 0
	global_load_lds_dwordx4 v139, s[20:21]
	s_mov_b32 m0, s71
	s_add_u32 s74, s20, 0x80000
	s_mov_b32 s71, m0
	s_mov_b32 m0, s36
	s_nop 0
	global_load_lds_dwordx4 v141, s[20:21]
	s_mov_b32 m0, s71
	s_addc_u32 s75, s21, 0
	s_mov_b32 s71, m0
	s_mov_b32 m0, s37
	s_nop 0
	global_load_lds_dwordx4 v139, s[74:75]
	s_mov_b32 m0, s71
	s_nop 0
	s_mov_b32 s71, m0
	s_mov_b32 m0, s40
	s_nop 0
	global_load_lds_dwordx4 v141, s[74:75]
	s_mov_b32 m0, s71
	s_waitcnt vmcnt(4)
	s_waitcnt lgkmcnt(0)
	s_barrier
	s_setprio 1
	s_waitcnt lgkmcnt(7)
	v_mfma_f32_16x16x32_bf16 v[62:65], v[148:151], v[182:185], 0
	v_mfma_f32_16x16x32_bf16 v[62:65], v[152:155], v[186:189], v[62:65]
	s_waitcnt lgkmcnt(5)
	v_mfma_f32_16x16x32_bf16 v[58:61], v[156:159], v[182:185], 0
	v_mfma_f32_16x16x32_bf16 v[58:61], v[160:163], v[186:189], v[58:61]
	s_waitcnt lgkmcnt(3)
	v_mfma_f32_16x16x32_bf16 v[42:45], v[156:159], v[190:193], 0
	v_mfma_f32_16x16x32_bf16 v[42:45], v[160:163], v[194:197], v[42:45]
	s_waitcnt lgkmcnt(1)
	v_mfma_f32_16x16x32_bf16 v[46:49], v[148:151], v[190:193], 0
	v_mfma_f32_16x16x32_bf16 v[46:49], v[152:155], v[194:197], v[46:49]
	v_mfma_f32_16x16x32_bf16 v[30:33], v[148:151], v[198:201], 0
	v_mfma_f32_16x16x32_bf16 v[30:33], v[152:155], v[202:205], v[30:33]
	v_mfma_f32_16x16x32_bf16 v[26:29], v[156:159], v[198:201], 0
	v_mfma_f32_16x16x32_bf16 v[26:29], v[160:163], v[202:205], v[26:29]
	v_mfma_f32_16x16x32_bf16 v[10:13], v[156:159], v[206:209], 0
	v_mfma_f32_16x16x32_bf16 v[10:13], v[160:163], v[210:213], v[10:13]
	s_waitcnt lgkmcnt(0)
	v_mfma_f32_16x16x32_bf16 v[14:17], v[148:151], v[206:209], 0
	v_mfma_f32_16x16x32_bf16 v[14:17], v[152:155], v[210:213], v[14:17]
	s_setprio 0
	s_setprio 1
	v_mfma_f32_16x16x32_bf16 v[54:57], v[164:167], v[182:185], 0
	v_mfma_f32_16x16x32_bf16 v[54:57], v[168:171], v[186:189], v[54:57]
	v_mfma_f32_16x16x32_bf16 v[50:53], v[172:175], v[182:185], 0
	v_mfma_f32_16x16x32_bf16 v[50:53], v[176:179], v[186:189], v[50:53]
	v_mfma_f32_16x16x32_bf16 v[34:37], v[172:175], v[190:193], 0
	v_mfma_f32_16x16x32_bf16 v[34:37], v[176:179], v[194:197], v[34:37]
	v_mfma_f32_16x16x32_bf16 v[38:41], v[164:167], v[190:193], 0
	v_mfma_f32_16x16x32_bf16 v[38:41], v[168:171], v[194:197], v[38:41]
	v_mfma_f32_16x16x32_bf16 v[22:25], v[164:167], v[198:201], 0
	v_mfma_f32_16x16x32_bf16 v[22:25], v[168:171], v[202:205], v[22:25]
	v_mfma_f32_16x16x32_bf16 v[18:21], v[172:175], v[198:201], 0
	v_mfma_f32_16x16x32_bf16 v[18:21], v[176:179], v[202:205], v[18:21]
	v_mfma_f32_16x16x32_bf16 v[2:5], v[172:175], v[206:209], 0
	v_mfma_f32_16x16x32_bf16 v[2:5], v[176:179], v[210:213], v[2:5]
	s_setprio 2
	s_barrier
	v_mfma_f32_16x16x32_bf16 v[6:9], v[164:167], v[206:209], 0
	v_mfma_f32_16x16x32_bf16 v[6:9], v[168:171], v[210:213], v[6:9]
	s_setprio 0
	ds_read_b128 v[148:151], v146
	ds_read_b128 v[152:155], v146 offset:1024
	ds_read_b128 v[156:159], v146 offset:2048
	ds_read_b128 v[160:163], v146 offset:3072
	ds_read_b128 v[164:167], v147
	ds_read_b128 v[168:171], v147 offset:1024
	ds_read_b128 v[172:175], v147 offset:2048
	ds_read_b128 v[176:179], v147 offset:3072
	ds_read_b128 v[182:185], v145 offset:32768
	ds_read_b128 v[186:189], v145 offset:33792
	ds_read_b128 v[190:193], v145 offset:34816
	ds_read_b128 v[194:197], v145 offset:35840
	ds_read_b128 v[198:201], v145 offset:36864
	ds_read_b128 v[202:205], v145 offset:37888
	ds_read_b128 v[206:209], v145 offset:38912
	ds_read_b128 v[210:213], v145 offset:39936
	s_mov_b32 s71, m0
	s_mov_b32 m0, s31
	s_nop 0
	global_load_lds_dwordx4 v138, s[22:23]
	s_mov_b32 m0, s71
	s_nop 0
	s_mov_b32 s71, m0
	s_mov_b32 m0, s41
	s_nop 0
	global_load_lds_dwordx4 v140, s[22:23]
	s_mov_b32 m0, s71
	s_add_u32 s22, s22, 0x80000
	s_addc_u32 s23, s23, 0
	s_mov_b32 s71, m0
	s_mov_b32 m0, s42
	s_nop 0
	global_load_lds_dwordx4 v138, s[22:23]
	s_mov_b32 m0, s71
	s_nop 0
	s_mov_b32 s71, m0
	s_mov_b32 m0, s43
	s_nop 0
	global_load_lds_dwordx4 v140, s[22:23]
	s_mov_b32 m0, s71
	s_waitcnt vmcnt(8)
	s_waitcnt lgkmcnt(0)
	s_barrier
	s_setprio 1
	s_waitcnt lgkmcnt(7)
	v_mfma_f32_16x16x32_bf16 v[126:129], v[148:151], v[182:185], v[126:129]
	v_mfma_f32_16x16x32_bf16 v[126:129], v[152:155], v[186:189], v[126:129]
	s_waitcnt lgkmcnt(5)
	v_mfma_f32_16x16x32_bf16 v[122:125], v[156:159], v[182:185], v[122:125]
	v_mfma_f32_16x16x32_bf16 v[122:125], v[160:163], v[186:189], v[122:125]
	s_waitcnt lgkmcnt(3)
	v_mfma_f32_16x16x32_bf16 v[106:109], v[156:159], v[190:193], v[106:109]
	v_mfma_f32_16x16x32_bf16 v[106:109], v[160:163], v[194:197], v[106:109]
	s_waitcnt lgkmcnt(1)
	v_mfma_f32_16x16x32_bf16 v[110:113], v[148:151], v[190:193], v[110:113]
	v_mfma_f32_16x16x32_bf16 v[110:113], v[152:155], v[194:197], v[110:113]
	v_mfma_f32_16x16x32_bf16 v[94:97], v[148:151], v[198:201], v[94:97]
	v_mfma_f32_16x16x32_bf16 v[94:97], v[152:155], v[202:205], v[94:97]
	v_mfma_f32_16x16x32_bf16 v[90:93], v[156:159], v[198:201], v[90:93]
	v_mfma_f32_16x16x32_bf16 v[90:93], v[160:163], v[202:205], v[90:93]
	v_mfma_f32_16x16x32_bf16 v[74:77], v[156:159], v[206:209], v[74:77]
	v_mfma_f32_16x16x32_bf16 v[74:77], v[160:163], v[210:213], v[74:77]
	s_waitcnt lgkmcnt(0)
	v_mfma_f32_16x16x32_bf16 v[78:81], v[148:151], v[206:209], v[78:81]
	v_mfma_f32_16x16x32_bf16 v[78:81], v[152:155], v[210:213], v[78:81]
	s_setprio 0
	s_setprio 1
	v_mfma_f32_16x16x32_bf16 v[118:121], v[164:167], v[182:185], v[118:121]
	v_mfma_f32_16x16x32_bf16 v[118:121], v[168:171], v[186:189], v[118:121]
	v_mfma_f32_16x16x32_bf16 v[114:117], v[172:175], v[182:185], v[114:117]
	v_mfma_f32_16x16x32_bf16 v[114:117], v[176:179], v[186:189], v[114:117]
	v_mfma_f32_16x16x32_bf16 v[98:101], v[172:175], v[190:193], v[98:101]
	v_mfma_f32_16x16x32_bf16 v[98:101], v[176:179], v[194:197], v[98:101]
	v_mfma_f32_16x16x32_bf16 v[102:105], v[164:167], v[190:193], v[102:105]
	v_mfma_f32_16x16x32_bf16 v[102:105], v[168:171], v[194:197], v[102:105]
	v_mfma_f32_16x16x32_bf16 v[86:89], v[164:167], v[198:201], v[86:89]
	v_mfma_f32_16x16x32_bf16 v[86:89], v[168:171], v[202:205], v[86:89]
	v_mfma_f32_16x16x32_bf16 v[82:85], v[172:175], v[198:201], v[82:85]
	v_mfma_f32_16x16x32_bf16 v[82:85], v[176:179], v[202:205], v[82:85]
	v_mfma_f32_16x16x32_bf16 v[66:69], v[172:175], v[206:209], v[66:69]
	v_mfma_f32_16x16x32_bf16 v[66:69], v[176:179], v[210:213], v[66:69]
	s_setprio 2
	s_barrier
	v_mfma_f32_16x16x32_bf16 v[70:73], v[164:167], v[206:209], v[70:73]
	v_mfma_f32_16x16x32_bf16 v[70:73], v[168:171], v[210:213], v[70:73]
	s_setprio 0
	ds_read_b128 v[182:185], v145 offset:49152
	ds_read_b128 v[186:189], v145 offset:50176
	ds_read_b128 v[190:193], v145 offset:51200
	ds_read_b128 v[194:197], v145 offset:52224
	ds_read_b128 v[198:201], v145 offset:53248
	ds_read_b128 v[202:205], v145 offset:54272
	ds_read_b128 v[206:209], v145 offset:55296
	ds_read_b128 v[210:213], v145 offset:56320
	s_add_u32 s22, s20, 0x80
	s_addc_u32 s23, s21, 0
	s_mov_b32 s71, m0
	s_mov_b32 m0, s44
	s_nop 0
	global_load_lds_dwordx4 v139, s[22:23]
	s_mov_b32 m0, s71
	s_add_u32 s20, s20, 0x80080
	s_mov_b32 s71, m0
	s_mov_b32 m0, s45
	s_nop 0
	global_load_lds_dwordx4 v141, s[22:23]
	s_mov_b32 m0, s71
	s_addc_u32 s21, s21, 0
	s_mov_b32 s22, m0
	s_mov_b32 m0, s46
	s_nop 0
	global_load_lds_dwordx4 v139, s[20:21]
	s_mov_b32 m0, s22
	s_nop 0
	s_mov_b32 s22, m0
	s_mov_b32 m0, s47
	s_nop 0
	global_load_lds_dwordx4 v141, s[20:21]
	s_mov_b32 m0, s22
	s_waitcnt vmcnt(4)
	s_waitcnt lgkmcnt(0)
	s_barrier
	s_setprio 1
	s_waitcnt lgkmcnt(7)
	v_mfma_f32_16x16x32_bf16 v[62:65], v[148:151], v[182:185], v[62:65]
	v_mfma_f32_16x16x32_bf16 v[62:65], v[152:155], v[186:189], v[62:65]
	s_waitcnt lgkmcnt(5)
	v_mfma_f32_16x16x32_bf16 v[58:61], v[156:159], v[182:185], v[58:61]
	v_mfma_f32_16x16x32_bf16 v[58:61], v[160:163], v[186:189], v[58:61]
	s_waitcnt lgkmcnt(3)
	v_mfma_f32_16x16x32_bf16 v[42:45], v[156:159], v[190:193], v[42:45]
	v_mfma_f32_16x16x32_bf16 v[42:45], v[160:163], v[194:197], v[42:45]
	s_waitcnt lgkmcnt(1)
	v_mfma_f32_16x16x32_bf16 v[46:49], v[148:151], v[190:193], v[46:49]
	v_mfma_f32_16x16x32_bf16 v[46:49], v[152:155], v[194:197], v[46:49]
	v_mfma_f32_16x16x32_bf16 v[30:33], v[148:151], v[198:201], v[30:33]
	v_mfma_f32_16x16x32_bf16 v[30:33], v[152:155], v[202:205], v[30:33]
	v_mfma_f32_16x16x32_bf16 v[26:29], v[156:159], v[198:201], v[26:29]
	v_mfma_f32_16x16x32_bf16 v[26:29], v[160:163], v[202:205], v[26:29]
	v_mfma_f32_16x16x32_bf16 v[10:13], v[156:159], v[206:209], v[10:13]
	v_mfma_f32_16x16x32_bf16 v[10:13], v[160:163], v[210:213], v[10:13]
	s_waitcnt lgkmcnt(0)
	v_mfma_f32_16x16x32_bf16 v[14:17], v[148:151], v[206:209], v[14:17]
	v_mfma_f32_16x16x32_bf16 v[14:17], v[152:155], v[210:213], v[14:17]
	s_setprio 0
	s_setprio 1
	v_mfma_f32_16x16x32_bf16 v[54:57], v[164:167], v[182:185], v[54:57]
	v_mfma_f32_16x16x32_bf16 v[54:57], v[168:171], v[186:189], v[54:57]
	v_mfma_f32_16x16x32_bf16 v[50:53], v[172:175], v[182:185], v[50:53]
	v_mfma_f32_16x16x32_bf16 v[50:53], v[176:179], v[186:189], v[50:53]
	v_mfma_f32_16x16x32_bf16 v[34:37], v[172:175], v[190:193], v[34:37]
	v_mfma_f32_16x16x32_bf16 v[34:37], v[176:179], v[194:197], v[34:37]
	v_mfma_f32_16x16x32_bf16 v[38:41], v[164:167], v[190:193], v[38:41]
	v_mfma_f32_16x16x32_bf16 v[38:41], v[168:171], v[194:197], v[38:41]
	v_mfma_f32_16x16x32_bf16 v[22:25], v[164:167], v[198:201], v[22:25]
	v_mfma_f32_16x16x32_bf16 v[22:25], v[168:171], v[202:205], v[22:25]
	v_mfma_f32_16x16x32_bf16 v[18:21], v[172:175], v[198:201], v[18:21]
	v_mfma_f32_16x16x32_bf16 v[18:21], v[176:179], v[202:205], v[18:21]
	v_mfma_f32_16x16x32_bf16 v[2:5], v[172:175], v[206:209], v[2:5]
	v_mfma_f32_16x16x32_bf16 v[2:5], v[176:179], v[210:213], v[2:5]
	s_setprio 2
	s_barrier
	v_mfma_f32_16x16x32_bf16 v[6:9], v[164:167], v[206:209], v[6:9]
	v_mfma_f32_16x16x32_bf16 v[6:9], v[168:171], v[210:213], v[6:9]
	s_setprio 0
	s_add_i32 s70, s70, 2
	s_add_u32 s64, s64, 0x100
	s_addc_u32 s65, s65, 0
	s_add_u32 s18, s18, 0x100
	s_addc_u32 s19, s19, 0
	s_add_u32 s66, s66, 0x100
	s_addc_u32 s67, s67, 0
	s_cmp_gt_u32 s70, 29
	.p2align 6
.LBB0_2594:
	ds_read_b128 v[148:151], v143
	ds_read_b128 v[152:155], v143 offset:1024
	ds_read_b128 v[156:159], v143 offset:2048
	ds_read_b128 v[160:163], v143 offset:3072
	ds_read_b128 v[164:167], v144
	ds_read_b128 v[168:171], v144 offset:1024
	ds_read_b128 v[172:175], v144 offset:2048
	ds_read_b128 v[176:179], v144 offset:3072
	s_cmp_eq_u32 s70, 28
	s_cselect_b32 s21, s9, s65
	s_cselect_b32 s20, s63, s64
	s_cselect_b32 s23, s11, s67
	s_cselect_b32 s22, s62, s66
	ds_read_b128 v[182:185], v145
	ds_read_b128 v[186:189], v145 offset:1024
	ds_read_b128 v[190:193], v145 offset:2048
	ds_read_b128 v[194:197], v145 offset:3072
	ds_read_b128 v[198:201], v145 offset:4096
	ds_read_b128 v[202:205], v145 offset:5120
	ds_read_b128 v[206:209], v145 offset:6144
	ds_read_b128 v[210:213], v145 offset:7168
	s_add_u32 s74, s18, 0xfff80000
	s_addc_u32 s75, s19, -1
	s_mov_b32 s71, m0
	s_mov_b32 m0, s48
	s_nop 0
	global_load_lds_dwordx4 v138, s[74:75]
	s_mov_b32 m0, s71
	s_nop 0
	s_mov_b32 s71, m0
	s_mov_b32 m0, s57
	s_nop 0
	global_load_lds_dwordx4 v140, s[74:75]
	s_mov_b32 m0, s71
	s_nop 0
	s_mov_b32 s71, m0
	s_mov_b32 m0, s49
	s_nop 0
	global_load_lds_dwordx4 v138, s[18:19]
	s_mov_b32 m0, s71
	s_nop 0
	s_mov_b32 s71, m0
	s_mov_b32 m0, s58
	s_nop 0
	global_load_lds_dwordx4 v140, s[18:19]
	s_mov_b32 m0, s71
	s_waitcnt vmcnt(8)
	s_waitcnt lgkmcnt(0)
	s_barrier
	s_setprio 1
	s_waitcnt lgkmcnt(7)
	v_mfma_f32_16x16x32_bf16 v[126:129], v[148:151], v[182:185], v[126:129]
	v_mfma_f32_16x16x32_bf16 v[126:129], v[152:155], v[186:189], v[126:129]
	s_waitcnt lgkmcnt(5)
	v_mfma_f32_16x16x32_bf16 v[122:125], v[156:159], v[182:185], v[122:125]
	v_mfma_f32_16x16x32_bf16 v[122:125], v[160:163], v[186:189], v[122:125]
	s_waitcnt lgkmcnt(3)
	v_mfma_f32_16x16x32_bf16 v[106:109], v[156:159], v[190:193], v[106:109]
	v_mfma_f32_16x16x32_bf16 v[106:109], v[160:163], v[194:197], v[106:109]
	s_waitcnt lgkmcnt(1)
	v_mfma_f32_16x16x32_bf16 v[110:113], v[148:151], v[190:193], v[110:113]
	v_mfma_f32_16x16x32_bf16 v[110:113], v[152:155], v[194:197], v[110:113]
	v_mfma_f32_16x16x32_bf16 v[94:97], v[148:151], v[198:201], v[94:97]
	v_mfma_f32_16x16x32_bf16 v[94:97], v[152:155], v[202:205], v[94:97]
	v_mfma_f32_16x16x32_bf16 v[90:93], v[156:159], v[198:201], v[90:93]
	v_mfma_f32_16x16x32_bf16 v[90:93], v[160:163], v[202:205], v[90:93]
	v_mfma_f32_16x16x32_bf16 v[74:77], v[156:159], v[206:209], v[74:77]
	v_mfma_f32_16x16x32_bf16 v[74:77], v[160:163], v[210:213], v[74:77]
	s_waitcnt lgkmcnt(0)
	v_mfma_f32_16x16x32_bf16 v[78:81], v[148:151], v[206:209], v[78:81]
	v_mfma_f32_16x16x32_bf16 v[78:81], v[152:155], v[210:213], v[78:81]
	s_setprio 0
	s_setprio 1
	v_mfma_f32_16x16x32_bf16 v[118:121], v[164:167], v[182:185], v[118:121]
	v_mfma_f32_16x16x32_bf16 v[118:121], v[168:171], v[186:189], v[118:121]
	v_mfma_f32_16x16x32_bf16 v[114:117], v[172:175], v[182:185], v[114:117]
	v_mfma_f32_16x16x32_bf16 v[114:117], v[176:179], v[186:189], v[114:117]
	v_mfma_f32_16x16x32_bf16 v[98:101], v[172:175], v[190:193], v[98:101]
	v_mfma_f32_16x16x32_bf16 v[98:101], v[176:179], v[194:197], v[98:101]
	v_mfma_f32_16x16x32_bf16 v[102:105], v[164:167], v[190:193], v[102:105]
	v_mfma_f32_16x16x32_bf16 v[102:105], v[168:171], v[194:197], v[102:105]
	v_mfma_f32_16x16x32_bf16 v[86:89], v[164:167], v[198:201], v[86:89]
	v_mfma_f32_16x16x32_bf16 v[86:89], v[168:171], v[202:205], v[86:89]
	v_mfma_f32_16x16x32_bf16 v[82:85], v[172:175], v[198:201], v[82:85]
	v_mfma_f32_16x16x32_bf16 v[82:85], v[176:179], v[202:205], v[82:85]
	v_mfma_f32_16x16x32_bf16 v[66:69], v[172:175], v[206:209], v[66:69]
	v_mfma_f32_16x16x32_bf16 v[66:69], v[176:179], v[210:213], v[66:69]
	s_setprio 2
	s_barrier
	v_mfma_f32_16x16x32_bf16 v[70:73], v[164:167], v[206:209], v[70:73]
	v_mfma_f32_16x16x32_bf16 v[70:73], v[168:171], v[210:213], v[70:73]
	s_setprio 0
	ds_read_b128 v[182:185], v145 offset:16384
	ds_read_b128 v[186:189], v145 offset:17408
	ds_read_b128 v[190:193], v145 offset:18432
	ds_read_b128 v[194:197], v145 offset:19456
	ds_read_b128 v[198:201], v145 offset:20480
	ds_read_b128 v[202:205], v145 offset:21504
	ds_read_b128 v[206:209], v145 offset:22528
	ds_read_b128 v[210:213], v145 offset:23552
	s_mov_b32 s71, m0
	s_mov_b32 m0, s35
	s_nop 0
	global_load_lds_dwordx4 v139, s[20:21]
	s_mov_b32 m0, s71
	s_add_u32 s74, s20, 0x80000
	s_mov_b32 s71, m0
	s_mov_b32 m0, s36
	s_nop 0
	global_load_lds_dwordx4 v141, s[20:21]
	s_mov_b32 m0, s71
	s_addc_u32 s75, s21, 0
	s_mov_b32 s71, m0
	s_mov_b32 m0, s37
	s_nop 0
	global_load_lds_dwordx4 v139, s[74:75]
	s_mov_b32 m0, s71
	s_nop 0
	s_mov_b32 s71, m0
	s_mov_b32 m0, s40
	s_nop 0
	global_load_lds_dwordx4 v141, s[74:75]
	s_mov_b32 m0, s71
	s_waitcnt vmcnt(4)
	s_waitcnt lgkmcnt(0)
	s_barrier
	s_setprio 1
	s_waitcnt lgkmcnt(7)
	v_mfma_f32_16x16x32_bf16 v[62:65], v[148:151], v[182:185], v[62:65]
	v_mfma_f32_16x16x32_bf16 v[62:65], v[152:155], v[186:189], v[62:65]
	s_waitcnt lgkmcnt(5)
	v_mfma_f32_16x16x32_bf16 v[58:61], v[156:159], v[182:185], v[58:61]
	v_mfma_f32_16x16x32_bf16 v[58:61], v[160:163], v[186:189], v[58:61]
	s_waitcnt lgkmcnt(3)
	v_mfma_f32_16x16x32_bf16 v[42:45], v[156:159], v[190:193], v[42:45]
	v_mfma_f32_16x16x32_bf16 v[42:45], v[160:163], v[194:197], v[42:45]
	s_waitcnt lgkmcnt(1)
	v_mfma_f32_16x16x32_bf16 v[46:49], v[148:151], v[190:193], v[46:49]
	v_mfma_f32_16x16x32_bf16 v[46:49], v[152:155], v[194:197], v[46:49]
	v_mfma_f32_16x16x32_bf16 v[30:33], v[148:151], v[198:201], v[30:33]
	v_mfma_f32_16x16x32_bf16 v[30:33], v[152:155], v[202:205], v[30:33]
	v_mfma_f32_16x16x32_bf16 v[26:29], v[156:159], v[198:201], v[26:29]
	v_mfma_f32_16x16x32_bf16 v[26:29], v[160:163], v[202:205], v[26:29]
	v_mfma_f32_16x16x32_bf16 v[10:13], v[156:159], v[206:209], v[10:13]
	v_mfma_f32_16x16x32_bf16 v[10:13], v[160:163], v[210:213], v[10:13]
	s_waitcnt lgkmcnt(0)
	v_mfma_f32_16x16x32_bf16 v[14:17], v[148:151], v[206:209], v[14:17]
	v_mfma_f32_16x16x32_bf16 v[14:17], v[152:155], v[210:213], v[14:17]
	s_setprio 0
	s_setprio 1
	v_mfma_f32_16x16x32_bf16 v[54:57], v[164:167], v[182:185], v[54:57]
	v_mfma_f32_16x16x32_bf16 v[54:57], v[168:171], v[186:189], v[54:57]
	v_mfma_f32_16x16x32_bf16 v[50:53], v[172:175], v[182:185], v[50:53]
	v_mfma_f32_16x16x32_bf16 v[50:53], v[176:179], v[186:189], v[50:53]
	v_mfma_f32_16x16x32_bf16 v[34:37], v[172:175], v[190:193], v[34:37]
	v_mfma_f32_16x16x32_bf16 v[34:37], v[176:179], v[194:197], v[34:37]
	v_mfma_f32_16x16x32_bf16 v[38:41], v[164:167], v[190:193], v[38:41]
	v_mfma_f32_16x16x32_bf16 v[38:41], v[168:171], v[194:197], v[38:41]
	v_mfma_f32_16x16x32_bf16 v[22:25], v[164:167], v[198:201], v[22:25]
	v_mfma_f32_16x16x32_bf16 v[22:25], v[168:171], v[202:205], v[22:25]
	v_mfma_f32_16x16x32_bf16 v[18:21], v[172:175], v[198:201], v[18:21]
	v_mfma_f32_16x16x32_bf16 v[18:21], v[176:179], v[202:205], v[18:21]
	v_mfma_f32_16x16x32_bf16 v[2:5], v[172:175], v[206:209], v[2:5]
	v_mfma_f32_16x16x32_bf16 v[2:5], v[176:179], v[210:213], v[2:5]
	s_setprio 2
	s_barrier
	v_mfma_f32_16x16x32_bf16 v[6:9], v[164:167], v[206:209], v[6:9]
	v_mfma_f32_16x16x32_bf16 v[6:9], v[168:171], v[210:213], v[6:9]
	s_setprio 0
	ds_read_b128 v[148:151], v146
	ds_read_b128 v[152:155], v146 offset:1024
	ds_read_b128 v[156:159], v146 offset:2048
	ds_read_b128 v[160:163], v146 offset:3072
	ds_read_b128 v[164:167], v147
	ds_read_b128 v[168:171], v147 offset:1024
	ds_read_b128 v[172:175], v147 offset:2048
	ds_read_b128 v[176:179], v147 offset:3072
	ds_read_b128 v[182:185], v145 offset:32768
	ds_read_b128 v[186:189], v145 offset:33792
	ds_read_b128 v[190:193], v145 offset:34816
	ds_read_b128 v[194:197], v145 offset:35840
	ds_read_b128 v[198:201], v145 offset:36864
	ds_read_b128 v[202:205], v145 offset:37888
	ds_read_b128 v[206:209], v145 offset:38912
	ds_read_b128 v[210:213], v145 offset:39936
	s_mov_b32 s71, m0
	s_mov_b32 m0, s31
	s_nop 0
	global_load_lds_dwordx4 v138, s[22:23]
	s_mov_b32 m0, s71
	s_nop 0
	s_mov_b32 s71, m0
	s_mov_b32 m0, s41
	s_nop 0
	global_load_lds_dwordx4 v140, s[22:23]
	s_mov_b32 m0, s71
	s_add_u32 s22, s22, 0x80000
	s_addc_u32 s23, s23, 0
	s_mov_b32 s71, m0
	s_mov_b32 m0, s42
	s_nop 0
	global_load_lds_dwordx4 v138, s[22:23]
	s_mov_b32 m0, s71
	s_nop 0
	s_mov_b32 s71, m0
	s_mov_b32 m0, s43
	s_nop 0
	global_load_lds_dwordx4 v140, s[22:23]
	s_mov_b32 m0, s71
	s_waitcnt vmcnt(8)
	s_waitcnt lgkmcnt(0)
	s_barrier
	s_setprio 1
	s_waitcnt lgkmcnt(7)
	v_mfma_f32_16x16x32_bf16 v[126:129], v[148:151], v[182:185], v[126:129]
	v_mfma_f32_16x16x32_bf16 v[126:129], v[152:155], v[186:189], v[126:129]
	s_waitcnt lgkmcnt(5)
	v_mfma_f32_16x16x32_bf16 v[122:125], v[156:159], v[182:185], v[122:125]
	v_mfma_f32_16x16x32_bf16 v[122:125], v[160:163], v[186:189], v[122:125]
	s_waitcnt lgkmcnt(3)
	v_mfma_f32_16x16x32_bf16 v[106:109], v[156:159], v[190:193], v[106:109]
	v_mfma_f32_16x16x32_bf16 v[106:109], v[160:163], v[194:197], v[106:109]
	s_waitcnt lgkmcnt(1)
	v_mfma_f32_16x16x32_bf16 v[110:113], v[148:151], v[190:193], v[110:113]
	v_mfma_f32_16x16x32_bf16 v[110:113], v[152:155], v[194:197], v[110:113]
	v_mfma_f32_16x16x32_bf16 v[94:97], v[148:151], v[198:201], v[94:97]
	v_mfma_f32_16x16x32_bf16 v[94:97], v[152:155], v[202:205], v[94:97]
	v_mfma_f32_16x16x32_bf16 v[90:93], v[156:159], v[198:201], v[90:93]
	v_mfma_f32_16x16x32_bf16 v[90:93], v[160:163], v[202:205], v[90:93]
	v_mfma_f32_16x16x32_bf16 v[74:77], v[156:159], v[206:209], v[74:77]
	v_mfma_f32_16x16x32_bf16 v[74:77], v[160:163], v[210:213], v[74:77]
	s_waitcnt lgkmcnt(0)
	v_mfma_f32_16x16x32_bf16 v[78:81], v[148:151], v[206:209], v[78:81]
	v_mfma_f32_16x16x32_bf16 v[78:81], v[152:155], v[210:213], v[78:81]
	s_setprio 0
	s_setprio 1
	v_mfma_f32_16x16x32_bf16 v[118:121], v[164:167], v[182:185], v[118:121]
	v_mfma_f32_16x16x32_bf16 v[118:121], v[168:171], v[186:189], v[118:121]
	v_mfma_f32_16x16x32_bf16 v[114:117], v[172:175], v[182:185], v[114:117]
	v_mfma_f32_16x16x32_bf16 v[114:117], v[176:179], v[186:189], v[114:117]
	v_mfma_f32_16x16x32_bf16 v[98:101], v[172:175], v[190:193], v[98:101]
	v_mfma_f32_16x16x32_bf16 v[98:101], v[176:179], v[194:197], v[98:101]
	v_mfma_f32_16x16x32_bf16 v[102:105], v[164:167], v[190:193], v[102:105]
	v_mfma_f32_16x16x32_bf16 v[102:105], v[168:171], v[194:197], v[102:105]
	v_mfma_f32_16x16x32_bf16 v[86:89], v[164:167], v[198:201], v[86:89]
	v_mfma_f32_16x16x32_bf16 v[86:89], v[168:171], v[202:205], v[86:89]
	v_mfma_f32_16x16x32_bf16 v[82:85], v[172:175], v[198:201], v[82:85]
	v_mfma_f32_16x16x32_bf16 v[82:85], v[176:179], v[202:205], v[82:85]
	v_mfma_f32_16x16x32_bf16 v[66:69], v[172:175], v[206:209], v[66:69]
	v_mfma_f32_16x16x32_bf16 v[66:69], v[176:179], v[210:213], v[66:69]
	s_setprio 2
	s_barrier
	v_mfma_f32_16x16x32_bf16 v[70:73], v[164:167], v[206:209], v[70:73]
	v_mfma_f32_16x16x32_bf16 v[70:73], v[168:171], v[210:213], v[70:73]
	s_setprio 0
	ds_read_b128 v[182:185], v145 offset:49152
	ds_read_b128 v[186:189], v145 offset:50176
	ds_read_b128 v[190:193], v145 offset:51200
	ds_read_b128 v[194:197], v145 offset:52224
	ds_read_b128 v[198:201], v145 offset:53248
	ds_read_b128 v[202:205], v145 offset:54272
	ds_read_b128 v[206:209], v145 offset:55296
	ds_read_b128 v[210:213], v145 offset:56320
	s_add_u32 s22, s20, 0x80
	s_addc_u32 s23, s21, 0
	s_mov_b32 s71, m0
	s_mov_b32 m0, s44
	s_nop 0
	global_load_lds_dwordx4 v139, s[22:23]
	s_mov_b32 m0, s71
	s_add_u32 s20, s20, 0x80080
	s_mov_b32 s71, m0
	s_mov_b32 m0, s45
	s_nop 0
	global_load_lds_dwordx4 v141, s[22:23]
	s_mov_b32 m0, s71
	s_addc_u32 s21, s21, 0
	s_mov_b32 s22, m0
	s_mov_b32 m0, s46
	s_nop 0
	global_load_lds_dwordx4 v139, s[20:21]
	s_mov_b32 m0, s22
	s_nop 0
	s_mov_b32 s22, m0
	s_mov_b32 m0, s47
	s_nop 0
	global_load_lds_dwordx4 v141, s[20:21]
	s_mov_b32 m0, s22
	s_waitcnt vmcnt(4)
	s_waitcnt lgkmcnt(0)
	s_barrier
	s_setprio 1
	s_waitcnt lgkmcnt(7)
	v_mfma_f32_16x16x32_bf16 v[62:65], v[148:151], v[182:185], v[62:65]
	v_mfma_f32_16x16x32_bf16 v[62:65], v[152:155], v[186:189], v[62:65]
	s_waitcnt lgkmcnt(5)
	v_mfma_f32_16x16x32_bf16 v[58:61], v[156:159], v[182:185], v[58:61]
	v_mfma_f32_16x16x32_bf16 v[58:61], v[160:163], v[186:189], v[58:61]
	s_waitcnt lgkmcnt(3)
	v_mfma_f32_16x16x32_bf16 v[42:45], v[156:159], v[190:193], v[42:45]
	v_mfma_f32_16x16x32_bf16 v[42:45], v[160:163], v[194:197], v[42:45]
	s_waitcnt lgkmcnt(1)
	v_mfma_f32_16x16x32_bf16 v[46:49], v[148:151], v[190:193], v[46:49]
	v_mfma_f32_16x16x32_bf16 v[46:49], v[152:155], v[194:197], v[46:49]
	v_mfma_f32_16x16x32_bf16 v[30:33], v[148:151], v[198:201], v[30:33]
	v_mfma_f32_16x16x32_bf16 v[30:33], v[152:155], v[202:205], v[30:33]
	v_mfma_f32_16x16x32_bf16 v[26:29], v[156:159], v[198:201], v[26:29]
	v_mfma_f32_16x16x32_bf16 v[26:29], v[160:163], v[202:205], v[26:29]
	v_mfma_f32_16x16x32_bf16 v[10:13], v[156:159], v[206:209], v[10:13]
	v_mfma_f32_16x16x32_bf16 v[10:13], v[160:163], v[210:213], v[10:13]
	s_waitcnt lgkmcnt(0)
	v_mfma_f32_16x16x32_bf16 v[14:17], v[148:151], v[206:209], v[14:17]
	v_mfma_f32_16x16x32_bf16 v[14:17], v[152:155], v[210:213], v[14:17]
	s_setprio 0
	s_setprio 1
	v_mfma_f32_16x16x32_bf16 v[54:57], v[164:167], v[182:185], v[54:57]
	v_mfma_f32_16x16x32_bf16 v[54:57], v[168:171], v[186:189], v[54:57]
	v_mfma_f32_16x16x32_bf16 v[50:53], v[172:175], v[182:185], v[50:53]
	v_mfma_f32_16x16x32_bf16 v[50:53], v[176:179], v[186:189], v[50:53]
	v_mfma_f32_16x16x32_bf16 v[34:37], v[172:175], v[190:193], v[34:37]
	v_mfma_f32_16x16x32_bf16 v[34:37], v[176:179], v[194:197], v[34:37]
	v_mfma_f32_16x16x32_bf16 v[38:41], v[164:167], v[190:193], v[38:41]
	v_mfma_f32_16x16x32_bf16 v[38:41], v[168:171], v[194:197], v[38:41]
	v_mfma_f32_16x16x32_bf16 v[22:25], v[164:167], v[198:201], v[22:25]
	v_mfma_f32_16x16x32_bf16 v[22:25], v[168:171], v[202:205], v[22:25]
	v_mfma_f32_16x16x32_bf16 v[18:21], v[172:175], v[198:201], v[18:21]
	v_mfma_f32_16x16x32_bf16 v[18:21], v[176:179], v[202:205], v[18:21]
	v_mfma_f32_16x16x32_bf16 v[2:5], v[172:175], v[206:209], v[2:5]
	v_mfma_f32_16x16x32_bf16 v[2:5], v[176:179], v[210:213], v[2:5]
	s_setprio 2
	s_barrier
	v_mfma_f32_16x16x32_bf16 v[6:9], v[164:167], v[206:209], v[6:9]
	v_mfma_f32_16x16x32_bf16 v[6:9], v[168:171], v[210:213], v[6:9]
	s_setprio 0
	s_add_i32 s70, s70, 2
	s_add_u32 s64, s64, 0x100
	s_addc_u32 s65, s65, 0
	s_add_u32 s18, s18, 0x100
	s_addc_u32 s19, s19, 0
	s_add_u32 s66, s66, 0x100
	s_addc_u32 s67, s67, 0
	s_cmp_gt_u32 s70, 29
	s_cbranch_scc0 .LBB0_2594
	v_mov_b32_e32 v212, v252
	v_mov_b32_e32 v213, v253
	s_and_b64 vcc, exec, s[6:7]
	s_cbranch_vccz .LBB0_2597
	s_barrier

	.amdhsa_kernel _Z8mega_fwd4Args
		.amdhsa_group_segment_fixed_size 0
		.amdhsa_private_segment_fixed_size 0
		.amdhsa_kernarg_size 456
		.amdhsa_user_sgpr_count 2
		.amdhsa_user_sgpr_dispatch_ptr 0
		.amdhsa_user_sgpr_queue_ptr 0
		.amdhsa_user_sgpr_kernarg_segment_ptr 1
		.amdhsa_user_sgpr_dispatch_id 0
		.amdhsa_user_sgpr_kernarg_preload_length 0
		.amdhsa_user_sgpr_kernarg_preload_offset 0
		.amdhsa_user_sgpr_private_segment_size 0
		.amdhsa_uses_dynamic_stack 0
		.amdhsa_enable_private_segment 0
		.amdhsa_system_sgpr_workgroup_id_x 1
		.amdhsa_system_sgpr_workgroup_id_y 0
		.amdhsa_system_sgpr_workgroup_id_z 0
		.amdhsa_system_sgpr_workgroup_info 0
		.amdhsa_system_vgpr_workitem_id 0
		.amdhsa_next_free_vgpr 256
		.amdhsa_next_free_sgpr 98
		.amdhsa_accum_offset 256
		.amdhsa_reserve_vcc 1
		.amdhsa_float_round_mode_32 0
		.amdhsa_float_round_mode_16_64 0
		.amdhsa_float_denorm_mode_32 3
		.amdhsa_float_denorm_mode_16_64 3
		.amdhsa_dx10_clamp 1
		.amdhsa_ieee_mode 1
		.amdhsa_fp16_overflow 0
		.amdhsa_tg_split 0
		.amdhsa_exception_fp_ieee_invalid_op 0
		.amdhsa_exception_fp_denorm_src 0
		.amdhsa_exception_fp_ieee_div_zero 0
		.amdhsa_exception_fp_ieee_overflow 0
		.amdhsa_exception_fp_ieee_underflow 0
		.amdhsa_exception_fp_ieee_inexact 0
		.amdhsa_exception_int_div_zero 0
	.end_amdhsa_kernel

amdhsa.kernels:
  - .agpr_count:     0
    .args:
      - .offset:         0
        .size:           200
        .value_kind:     by_value
      - .offset:         200
        .size:           4
        .value_kind:     hidden_block_count_x
      - .offset:         204
        .size:           4
        .value_kind:     hidden_block_count_y
      - .offset:         208
        .size:           4
        .value_kind:     hidden_block_count_z
      - .offset:         212
        .size:           2
        .value_kind:     hidden_group_size_x
      - .offset:         214
        .size:           2
        .value_kind:     hidden_group_size_y
      - .offset:         216
        .size:           2
        .value_kind:     hidden_group_size_z
      - .offset:         218
        .size:           2
        .value_kind:     hidden_remainder_x
      - .offset:         220
        .size:           2
        .value_kind:     hidden_remainder_y
      - .offset:         222
        .size:           2
        .value_kind:     hidden_remainder_z
      - .offset:         240
        .size:           8
        .value_kind:     hidden_global_offset_x
      - .offset:         248
        .size:           8
        .value_kind:     hidden_global_offset_y
      - .offset:         256
        .size:           8
        .value_kind:     hidden_global_offset_z
      - .offset:         264
        .size:           2
        .value_kind:     hidden_grid_dims
      - .offset:         320
        .size:           4
        .value_kind:     hidden_dynamic_lds_size
    .group_segment_fixed_size: 0
    .kernarg_segment_align: 8
    .kernarg_segment_size: 456
    .language:       OpenCL C
    .language_version:
      - 2
      - 0
    .max_flat_workgroup_size: 512
    .name:           _Z8mega_fwd4Args
    .private_segment_fixed_size: 0
    .sgpr_count:     104
    .sgpr_spill_count: 22
    .symbol:         _Z8mega_fwd4Args.kd
    .uniform_work_group_size: 1
    .uses_dynamic_stack: false
    .vgpr_count:     256
    .vgpr_spill_count: 0
    .wavefront_size: 64
